# v092 with the rope sign-mask setup reordered: v_cmp vcc now 3 instructions ahead of the v_cndmask that reads it (hazard margin, no functional change)
# speedup vs baseline: 1.0034x; 1.0013x over previous
;     DI void operator()(const pg8::f32x4 (&acc)[2][2][4][2], const pg8::Unit& u, int wr, int wc, int fr, int fq) const {
;     ...
;                 const int pos = 16 + (tok & 4095), b = tok >> 12, s = tok & 4095;
; #pragma unroll
;                 for (int bj = 0; bj < 2; ++bj) {
;                     const int nb = nc0 + bj * 128 + wc * 32 + 8 * fq;
;                     float v[8];
; #pragma unroll
;                     for (int j = 0; j < 4; ++j) { v[j] = acc[ai][bj][m][0][j] * rsq; v[4 + j] = acc[ai][bj][m][1][j] * rsq; }
;                     if (do_rope) {
;                         const f32x4* cs = (const f32x4*)(rope + (size_t)pos * 16);
;                         const f32x4 c01 = cs[0], c23 = cs[1], c45 = cs[2], c67 = cs[3];
;                         const float cc[8] = {c01.x, c01.z, c23.x, c23.z, c45.x, c45.z, c67.x, c67.z};
;                         const float sn[8] = {c01.y, c01.w, c23.y, c23.w, c45.y, c45.w, c67.y, c67.w};
; #pragma unroll
;                         for (int j = 0; j < 8; ++j) {
;                             const float other = __shfl_xor(v[j], 16);
;                             const float r0 = v[j] * cc[j] - other * sn[j], r1 = v[j] * cc[j] + other * sn[j];
;                             v[j] = fq == 0 ? r0 : (fq == 1 ? r1 : v[j]);
;                         }
;                     }
.LBB0_301:
	v_bitop3_b32 v182, s74, v177, v167 bitop3:0xc8
	v_lshlrev_b32_e32 v152, 6, v182
	v_lshl_add_u64 v[136:137], s[70:71], 0, v[152:153]
	s_andn2_b64 vcc, exec, s[4:5]
	v_lshl_add_u64 v[160:161], v[136:137], 0, s[34:35]
	s_cbranch_vccnz .LBB0_351
	global_load_dwordx4 v[140:143], v[160:161], off offset:16
	global_load_dwordx4 v[0:3], v[160:161], off
	global_load_dwordx4 v[136:139], v[160:161], off offset:48
	global_load_dwordx4 v[4:7], v[160:161], off offset:32
	v_cmp_eq_u32_e32 vcc, 0, v168
	v_and_b32_e32 v237, 1, v168
	v_bfrev_b32_e32 v239, 1
	v_cmp_eq_u32_e64 s[4:5], 1, v237
	v_cmp_gt_u32_e64 s[78:79], 2, v168
	v_cndmask_b32_e32 v238, 0, v239, vcc
	v_mov_b32_e32 v248, v8
	v_mov_b32_e32 v252, v8
	v_mov_b32_e32 v249, v9
	v_mov_b32_e32 v253, v9
	v_mov_b32_e32 v250, v10
	v_mov_b32_e32 v254, v10
	v_mov_b32_e32 v251, v11
	v_mov_b32_e32 v255, v11
	v_permlane16_swap_b32_e32 v248, v252
	v_permlane16_swap_b32_e32 v249, v253
	v_permlane16_swap_b32_e32 v250, v254
	v_permlane16_swap_b32_e32 v251, v255
	s_nop 1
	v_cndmask_b32_e64 v248, v252, v248, s[4:5]
	v_cndmask_b32_e64 v249, v253, v249, s[4:5]
	v_cndmask_b32_e64 v250, v254, v250, s[4:5]
	v_cndmask_b32_e64 v251, v255, v251, s[4:5]
	s_waitcnt vmcnt(0)
	v_mul_f32_e32 v252, v8, v0
	v_xor_b32_e32 v237, v238, v1
	v_mul_f32_e32 v248, v248, v237
	v_add_f32_e32 v248, v252, v248
	v_cndmask_b32_e64 v8, v8, v248, s[78:79]
	v_mul_f32_e32 v253, v9, v2
	v_xor_b32_e32 v237, v238, v3
	v_mul_f32_e32 v249, v249, v237
	v_add_f32_e32 v249, v253, v249
	v_cndmask_b32_e64 v9, v9, v249, s[78:79]
	v_mul_f32_e32 v254, v10, v140
	v_xor_b32_e32 v237, v238, v141
	v_mul_f32_e32 v250, v250, v237
	v_add_f32_e32 v250, v254, v250
	v_cndmask_b32_e64 v10, v10, v250, s[78:79]
	v_mul_f32_e32 v255, v11, v142
	v_xor_b32_e32 v237, v238, v143
	v_mul_f32_e32 v251, v251, v237
	v_add_f32_e32 v251, v255, v251
	v_cndmask_b32_e64 v11, v11, v251, s[78:79]
	v_mov_b32_e32 v248, v12
	v_mov_b32_e32 v252, v12
	v_mov_b32_e32 v249, v13
	v_mov_b32_e32 v253, v13
	v_mov_b32_e32 v250, v14
	v_mov_b32_e32 v254, v14
	v_mov_b32_e32 v251, v15
	v_mov_b32_e32 v255, v15
	v_permlane16_swap_b32_e32 v248, v252
	v_permlane16_swap_b32_e32 v249, v253
	v_permlane16_swap_b32_e32 v250, v254
	v_permlane16_swap_b32_e32 v251, v255
	s_nop 1
	v_cndmask_b32_e64 v248, v252, v248, s[4:5]
	v_cndmask_b32_e64 v249, v253, v249, s[4:5]
	v_cndmask_b32_e64 v250, v254, v250, s[4:5]
	v_cndmask_b32_e64 v251, v255, v251, s[4:5]
	v_mul_f32_e32 v252, v12, v4
	v_xor_b32_e32 v237, v238, v5
	v_mul_f32_e32 v248, v248, v237
	v_add_f32_e32 v248, v252, v248
	v_cndmask_b32_e64 v12, v12, v248, s[78:79]
	v_mul_f32_e32 v253, v13, v6
	v_xor_b32_e32 v237, v238, v7
	v_mul_f32_e32 v249, v249, v237
	v_add_f32_e32 v249, v253, v249
	v_cndmask_b32_e64 v13, v13, v249, s[78:79]
	v_mul_f32_e32 v254, v14, v136
	v_xor_b32_e32 v237, v238, v137
	v_mul_f32_e32 v250, v250, v237
	v_add_f32_e32 v250, v254, v250
	v_cndmask_b32_e64 v14, v14, v250, s[78:79]
	v_mul_f32_e32 v255, v15, v138
	v_xor_b32_e32 v237, v238, v139
	v_mul_f32_e32 v251, v251, v237
	v_add_f32_e32 v251, v255, v251
	v_cndmask_b32_e64 v15, v15, v251, s[78:79]
	v_mov_b64_e32 v[0:1], v[8:9]
	v_mov_b64_e32 v[2:3], v[10:11]
	v_mov_b64_e32 v[4:5], v[12:13]
	v_mov_b64_e32 v[6:7], v[14:15]

;     DI void operator()(const pg8::f32x4 (&acc)[2][2][4][2], const pg8::Unit& u, int wr, int wc, int fr, int fq) const {
;     ...
;                     for (int j = 0; j < 4; ++j) { v[j] = acc[ai][bj][m][0][j] * rsq; v[4 + j] = acc[ai][bj][m][1][j] * rsq; }
;                     if (do_rope) {
;                         const f32x4* cs = (const f32x4*)(rope + (size_t)pos * 16);
;                         const f32x4 c01 = cs[0], c23 = cs[1], c45 = cs[2], c67 = cs[3];
;                         const float cc[8] = {c01.x, c01.z, c23.x, c23.z, c45.x, c45.z, c67.x, c67.z};
;                         const float sn[8] = {c01.y, c01.w, c23.y, c23.w, c45.y, c45.w, c67.y, c67.w};
; #pragma unroll
;                         for (int j = 0; j < 8; ++j) {
;                             const float other = __shfl_xor(v[j], 16);
;                             const float r0 = v[j] * cc[j] - other * sn[j], r1 = v[j] * cc[j] + other * sn[j];
;                             v[j] = fq == 0 ? r0 : (fq == 1 ? r1 : v[j]);
;                         }
;                     }
.LBB0_373:
	s_andn2_b64 vcc, exec, s[8:9]
	s_cbranch_vccnz .LBB0_423
	global_load_dwordx4 v[132:135], v[160:161], off offset:16
	global_load_dwordx4 v[0:3], v[160:161], off
	global_load_dwordx4 v[128:131], v[160:161], off offset:48
	global_load_dwordx4 v[4:7], v[160:161], off offset:32
	v_cmp_eq_u32_e32 vcc, 0, v168
	v_and_b32_e32 v237, 1, v168
	v_bfrev_b32_e32 v239, 1
	v_cmp_eq_u32_e64 s[8:9], 1, v237
	v_cmp_gt_u32_e64 s[76:77], 2, v168
	v_cndmask_b32_e32 v238, 0, v239, vcc
	v_mov_b32_e32 v248, v8
	v_mov_b32_e32 v252, v8
	v_mov_b32_e32 v249, v9
	v_mov_b32_e32 v253, v9
	v_mov_b32_e32 v250, v10
	v_mov_b32_e32 v254, v10
	v_mov_b32_e32 v251, v11
	v_mov_b32_e32 v255, v11
	v_permlane16_swap_b32_e32 v248, v252
	v_permlane16_swap_b32_e32 v249, v253
	v_permlane16_swap_b32_e32 v250, v254
	v_permlane16_swap_b32_e32 v251, v255
	s_nop 1
	v_cndmask_b32_e64 v248, v252, v248, s[8:9]
	v_cndmask_b32_e64 v249, v253, v249, s[8:9]
	v_cndmask_b32_e64 v250, v254, v250, s[8:9]
	v_cndmask_b32_e64 v251, v255, v251, s[8:9]
	s_waitcnt vmcnt(0)
	v_mul_f32_e32 v252, v8, v0
	v_xor_b32_e32 v237, v238, v1
	v_mul_f32_e32 v248, v248, v237
	v_add_f32_e32 v248, v252, v248
	v_cndmask_b32_e64 v8, v8, v248, s[76:77]
	v_mul_f32_e32 v253, v9, v2
	v_xor_b32_e32 v237, v238, v3
	v_mul_f32_e32 v249, v249, v237
	v_add_f32_e32 v249, v253, v249
	v_cndmask_b32_e64 v9, v9, v249, s[76:77]
	v_mul_f32_e32 v254, v10, v132
	v_xor_b32_e32 v237, v238, v133
	v_mul_f32_e32 v250, v250, v237
	v_add_f32_e32 v250, v254, v250
	v_cndmask_b32_e64 v10, v10, v250, s[76:77]
	v_mul_f32_e32 v255, v11, v134
	v_xor_b32_e32 v237, v238, v135
	v_mul_f32_e32 v251, v251, v237
	v_add_f32_e32 v251, v255, v251
	v_cndmask_b32_e64 v11, v11, v251, s[76:77]
	v_mov_b32_e32 v248, v12
	v_mov_b32_e32 v252, v12
	v_mov_b32_e32 v249, v13
	v_mov_b32_e32 v253, v13
	v_mov_b32_e32 v250, v14
	v_mov_b32_e32 v254, v14
	v_mov_b32_e32 v251, v15
	v_mov_b32_e32 v255, v15
	v_permlane16_swap_b32_e32 v248, v252
	v_permlane16_swap_b32_e32 v249, v253
	v_permlane16_swap_b32_e32 v250, v254
	v_permlane16_swap_b32_e32 v251, v255
	s_nop 1
	v_cndmask_b32_e64 v248, v252, v248, s[8:9]
	v_cndmask_b32_e64 v249, v253, v249, s[8:9]
	v_cndmask_b32_e64 v250, v254, v250, s[8:9]
	v_cndmask_b32_e64 v251, v255, v251, s[8:9]
	v_mul_f32_e32 v252, v12, v4
	v_xor_b32_e32 v237, v238, v5
	v_mul_f32_e32 v248, v248, v237
	v_add_f32_e32 v248, v252, v248
	v_cndmask_b32_e64 v12, v12, v248, s[76:77]
	v_mul_f32_e32 v253, v13, v6
	v_xor_b32_e32 v237, v238, v7
	v_mul_f32_e32 v249, v249, v237
	v_add_f32_e32 v249, v253, v249
	v_cndmask_b32_e64 v13, v13, v249, s[76:77]
	v_mul_f32_e32 v254, v14, v128
	v_xor_b32_e32 v237, v238, v129
	v_mul_f32_e32 v250, v250, v237
	v_add_f32_e32 v250, v254, v250
	v_cndmask_b32_e64 v14, v14, v250, s[76:77]
	v_mul_f32_e32 v255, v15, v130
	v_xor_b32_e32 v237, v238, v131
	v_mul_f32_e32 v251, v251, v237
	v_add_f32_e32 v251, v255, v251
	v_cndmask_b32_e64 v15, v15, v251, s[76:77]
	v_mov_b64_e32 v[0:1], v[8:9]
	v_mov_b64_e32 v[2:3], v[10:11]
	v_mov_b64_e32 v[4:5], v[12:13]
	v_mov_b64_e32 v[6:7], v[14:15]

;     DI void operator()(const pg8::f32x4 (&acc)[2][2][4][2], const pg8::Unit& u, int wr, int wc, int fr, int fq) const {
;     ...
;                 const int pos = 16 + (tok & 4095), b = tok >> 12, s = tok & 4095;
; #pragma unroll
;                 for (int bj = 0; bj < 2; ++bj) {
;                     const int nb = nc0 + bj * 128 + wc * 32 + 8 * fq;
;                     float v[8];
; #pragma unroll
;                     for (int j = 0; j < 4; ++j) { v[j] = acc[ai][bj][m][0][j] * rsq; v[4 + j] = acc[ai][bj][m][1][j] * rsq; }
;                     if (do_rope) {
;                         const f32x4* cs = (const f32x4*)(rope + (size_t)pos * 16);
;                         const f32x4 c01 = cs[0], c23 = cs[1], c45 = cs[2], c67 = cs[3];
;                         const float cc[8] = {c01.x, c01.z, c23.x, c23.z, c45.x, c45.z, c67.x, c67.z};
;                         const float sn[8] = {c01.y, c01.w, c23.y, c23.w, c45.y, c45.w, c67.y, c67.w};
; #pragma unroll
;                         for (int j = 0; j < 8; ++j) {
;                             const float other = __shfl_xor(v[j], 16);
;                             const float r0 = v[j] * cc[j] - other * sn[j], r1 = v[j] * cc[j] + other * sn[j];
;                             v[j] = fq == 0 ? r0 : (fq == 1 ? r1 : v[j]);
;                         }
;                     }
.LBB0_445:
	v_bitop3_b32 v129, s74, v179, v171 bitop3:0xc8
	v_lshlrev_b32_e32 v152, 6, v129
	v_lshl_add_u64 v[120:121], s[70:71], 0, v[152:153]
	s_andn2_b64 vcc, exec, s[58:59]
	v_lshl_add_u64 v[132:133], v[120:121], 0, s[34:35]
	s_cbranch_vccnz .LBB0_495
	global_load_dwordx4 v[124:127], v[132:133], off offset:16
	global_load_dwordx4 v[0:3], v[132:133], off
	global_load_dwordx4 v[120:123], v[132:133], off offset:48
	global_load_dwordx4 v[4:7], v[132:133], off offset:32
	v_cmp_eq_u32_e32 vcc, 0, v168
	v_and_b32_e32 v237, 1, v168
	v_bfrev_b32_e32 v239, 1
	v_cmp_eq_u32_e64 s[52:53], 1, v237
	v_cmp_gt_u32_e64 s[58:59], 2, v168
	v_cndmask_b32_e32 v238, 0, v239, vcc
	v_mov_b32_e32 v248, v8
	v_mov_b32_e32 v252, v8
	v_mov_b32_e32 v249, v9
	v_mov_b32_e32 v253, v9
	v_mov_b32_e32 v250, v10
	v_mov_b32_e32 v254, v10
	v_mov_b32_e32 v251, v11
	v_mov_b32_e32 v255, v11
	v_permlane16_swap_b32_e32 v248, v252
	v_permlane16_swap_b32_e32 v249, v253
	v_permlane16_swap_b32_e32 v250, v254
	v_permlane16_swap_b32_e32 v251, v255
	s_nop 1
	v_cndmask_b32_e64 v248, v252, v248, s[52:53]
	v_cndmask_b32_e64 v249, v253, v249, s[52:53]
	v_cndmask_b32_e64 v250, v254, v250, s[52:53]
	v_cndmask_b32_e64 v251, v255, v251, s[52:53]
	s_waitcnt vmcnt(0)
	v_mul_f32_e32 v252, v8, v0
	v_xor_b32_e32 v237, v238, v1
	v_mul_f32_e32 v248, v248, v237
	v_add_f32_e32 v248, v252, v248
	v_cndmask_b32_e64 v8, v8, v248, s[58:59]
	v_mul_f32_e32 v253, v9, v2
	v_xor_b32_e32 v237, v238, v3
	v_mul_f32_e32 v249, v249, v237
	v_add_f32_e32 v249, v253, v249
	v_cndmask_b32_e64 v9, v9, v249, s[58:59]
	v_mul_f32_e32 v254, v10, v124
	v_xor_b32_e32 v237, v238, v125
	v_mul_f32_e32 v250, v250, v237
	v_add_f32_e32 v250, v254, v250
	v_cndmask_b32_e64 v10, v10, v250, s[58:59]
	v_mul_f32_e32 v255, v11, v126
	v_xor_b32_e32 v237, v238, v127
	v_mul_f32_e32 v251, v251, v237
	v_add_f32_e32 v251, v255, v251
	v_cndmask_b32_e64 v11, v11, v251, s[58:59]
	v_mov_b32_e32 v248, v12
	v_mov_b32_e32 v252, v12
	v_mov_b32_e32 v249, v13
	v_mov_b32_e32 v253, v13
	v_mov_b32_e32 v250, v14
	v_mov_b32_e32 v254, v14
	v_mov_b32_e32 v251, v15
	v_mov_b32_e32 v255, v15
	v_permlane16_swap_b32_e32 v248, v252
	v_permlane16_swap_b32_e32 v249, v253
	v_permlane16_swap_b32_e32 v250, v254
	v_permlane16_swap_b32_e32 v251, v255
	s_nop 1
	v_cndmask_b32_e64 v248, v252, v248, s[52:53]
	v_cndmask_b32_e64 v249, v253, v249, s[52:53]
	v_cndmask_b32_e64 v250, v254, v250, s[52:53]
	v_cndmask_b32_e64 v251, v255, v251, s[52:53]
	v_mul_f32_e32 v252, v12, v4
	v_xor_b32_e32 v237, v238, v5
	v_mul_f32_e32 v248, v248, v237
	v_add_f32_e32 v248, v252, v248
	v_cndmask_b32_e64 v12, v12, v248, s[58:59]
	v_mul_f32_e32 v253, v13, v6
	v_xor_b32_e32 v237, v238, v7
	v_mul_f32_e32 v249, v249, v237
	v_add_f32_e32 v249, v253, v249
	v_cndmask_b32_e64 v13, v13, v249, s[58:59]
	v_mul_f32_e32 v254, v14, v120
	v_xor_b32_e32 v237, v238, v121
	v_mul_f32_e32 v250, v250, v237
	v_add_f32_e32 v250, v254, v250
	v_cndmask_b32_e64 v14, v14, v250, s[58:59]
	v_mul_f32_e32 v255, v15, v122
	v_xor_b32_e32 v237, v238, v123
	v_mul_f32_e32 v251, v251, v237
	v_add_f32_e32 v251, v255, v251
	v_cndmask_b32_e64 v15, v15, v251, s[58:59]
	v_mov_b64_e32 v[0:1], v[8:9]
	v_mov_b64_e32 v[2:3], v[10:11]
	v_mov_b64_e32 v[4:5], v[12:13]
	v_mov_b64_e32 v[6:7], v[14:15]

;     DI void operator()(const pg8::f32x4 (&acc)[2][2][4][2], const pg8::Unit& u, int wr, int wc, int fr, int fq) const {
;     ...
;                     for (int j = 0; j < 4; ++j) { v[j] = acc[ai][bj][m][0][j] * rsq; v[4 + j] = acc[ai][bj][m][1][j] * rsq; }
;                     if (do_rope) {
;                         const f32x4* cs = (const f32x4*)(rope + (size_t)pos * 16);
;                         const f32x4 c01 = cs[0], c23 = cs[1], c45 = cs[2], c67 = cs[3];
;                         const float cc[8] = {c01.x, c01.z, c23.x, c23.z, c45.x, c45.z, c67.x, c67.z};
;                         const float sn[8] = {c01.y, c01.w, c23.y, c23.w, c45.y, c45.w, c67.y, c67.w};
; #pragma unroll
;                         for (int j = 0; j < 8; ++j) {
;                             const float other = __shfl_xor(v[j], 16);
;                             const float r0 = v[j] * cc[j] - other * sn[j], r1 = v[j] * cc[j] + other * sn[j];
;                             v[j] = fq == 0 ? r0 : (fq == 1 ? r1 : v[j]);
;                         }
;                     }
.LBB0_526:
	global_load_dwordx4 v[116:119], v[132:133], off offset:16
	global_load_dwordx4 v[0:3], v[132:133], off
	global_load_dwordx4 v[112:115], v[132:133], off offset:48
	global_load_dwordx4 v[4:7], v[132:133], off offset:32
	v_cmp_eq_u32_e32 vcc, 0, v168
	v_and_b32_e32 v237, 1, v168
	v_bfrev_b32_e32 v239, 1
	v_cmp_eq_u32_e64 s[52:53], 1, v237
	v_cmp_gt_u32_e64 s[58:59], 2, v168
	v_cndmask_b32_e32 v238, 0, v239, vcc
	v_mov_b32_e32 v248, v8
	v_mov_b32_e32 v252, v8
	v_mov_b32_e32 v249, v9
	v_mov_b32_e32 v253, v9
	v_mov_b32_e32 v250, v10
	v_mov_b32_e32 v254, v10
	v_mov_b32_e32 v251, v11
	v_mov_b32_e32 v255, v11
	v_permlane16_swap_b32_e32 v248, v252
	v_permlane16_swap_b32_e32 v249, v253
	v_permlane16_swap_b32_e32 v250, v254
	v_permlane16_swap_b32_e32 v251, v255
	s_nop 1
	v_cndmask_b32_e64 v248, v252, v248, s[52:53]
	v_cndmask_b32_e64 v249, v253, v249, s[52:53]
	v_cndmask_b32_e64 v250, v254, v250, s[52:53]
	v_cndmask_b32_e64 v251, v255, v251, s[52:53]
	s_waitcnt vmcnt(0)
	v_mul_f32_e32 v252, v8, v0
	v_xor_b32_e32 v237, v238, v1
	v_mul_f32_e32 v248, v248, v237
	v_add_f32_e32 v248, v252, v248
	v_cndmask_b32_e64 v8, v8, v248, s[58:59]
	v_mul_f32_e32 v253, v9, v2
	v_xor_b32_e32 v237, v238, v3
	v_mul_f32_e32 v249, v249, v237
	v_add_f32_e32 v249, v253, v249
	v_cndmask_b32_e64 v9, v9, v249, s[58:59]
	v_mul_f32_e32 v254, v10, v116
	v_xor_b32_e32 v237, v238, v117
	v_mul_f32_e32 v250, v250, v237
	v_add_f32_e32 v250, v254, v250
	v_cndmask_b32_e64 v10, v10, v250, s[58:59]
	v_mul_f32_e32 v255, v11, v118
	v_xor_b32_e32 v237, v238, v119
	v_mul_f32_e32 v251, v251, v237
	v_add_f32_e32 v251, v255, v251
	v_cndmask_b32_e64 v11, v11, v251, s[58:59]
	v_mov_b32_e32 v248, v12
	v_mov_b32_e32 v252, v12
	v_mov_b32_e32 v249, v13
	v_mov_b32_e32 v253, v13
	v_mov_b32_e32 v250, v14
	v_mov_b32_e32 v254, v14
	v_mov_b32_e32 v251, v15
	v_mov_b32_e32 v255, v15
	v_permlane16_swap_b32_e32 v248, v252
	v_permlane16_swap_b32_e32 v249, v253
	v_permlane16_swap_b32_e32 v250, v254
	v_permlane16_swap_b32_e32 v251, v255
	s_nop 1
	v_cndmask_b32_e64 v248, v252, v248, s[52:53]
	v_cndmask_b32_e64 v249, v253, v249, s[52:53]
	v_cndmask_b32_e64 v250, v254, v250, s[52:53]
	v_cndmask_b32_e64 v251, v255, v251, s[52:53]
	v_mul_f32_e32 v252, v12, v4
	v_xor_b32_e32 v237, v238, v5
	v_mul_f32_e32 v248, v248, v237
	v_add_f32_e32 v248, v252, v248
	v_cndmask_b32_e64 v12, v12, v248, s[58:59]
	v_mul_f32_e32 v253, v13, v6
	v_xor_b32_e32 v237, v238, v7
	v_mul_f32_e32 v249, v249, v237
	v_add_f32_e32 v249, v253, v249
	v_cndmask_b32_e64 v13, v13, v249, s[58:59]
	v_mul_f32_e32 v254, v14, v112
	v_xor_b32_e32 v237, v238, v113
	v_mul_f32_e32 v250, v250, v237
	v_add_f32_e32 v250, v254, v250
	v_cndmask_b32_e64 v14, v14, v250, s[58:59]
	v_mul_f32_e32 v255, v15, v114
	v_xor_b32_e32 v237, v238, v115
	v_mul_f32_e32 v251, v251, v237
	v_add_f32_e32 v251, v255, v251
	v_cndmask_b32_e64 v15, v15, v251, s[58:59]
	v_mov_b64_e32 v[0:1], v[8:9]
	v_mov_b64_e32 v[2:3], v[10:11]
	v_mov_b64_e32 v[4:5], v[12:13]
	v_mov_b64_e32 v[6:7], v[14:15]
	s_and_b64 vcc, exec, s[8:9]
	s_mov_b64 s[58:59], -1
	s_cbranch_vccz .LBB0_518

;     DI void operator()(const pg8::f32x4 (&acc)[2][2][4][2], const pg8::Unit& u, int wr, int wc, int fr, int fq) const {
;     ...
;                 const int pos = 16 + (tok & 4095), b = tok >> 12, s = tok & 4095;
; #pragma unroll
;                 for (int bj = 0; bj < 2; ++bj) {
;                     const int nb = nc0 + bj * 128 + wc * 32 + 8 * fq;
;                     float v[8];
; #pragma unroll
;                     for (int j = 0; j < 4; ++j) { v[j] = acc[ai][bj][m][0][j] * rsq; v[4 + j] = acc[ai][bj][m][1][j] * rsq; }
;                     if (do_rope) {
;                         const f32x4* cs = (const f32x4*)(rope + (size_t)pos * 16);
;                         const f32x4 c01 = cs[0], c23 = cs[1], c45 = cs[2], c67 = cs[3];
;                         const float cc[8] = {c01.x, c01.z, c23.x, c23.z, c45.x, c45.z, c67.x, c67.z};
;                         const float sn[8] = {c01.y, c01.w, c23.y, c23.w, c45.y, c45.w, c67.y, c67.w};
; #pragma unroll
;                         for (int j = 0; j < 8; ++j) {
;                             const float other = __shfl_xor(v[j], 16);
;                             const float r0 = v[j] * cc[j] - other * sn[j], r1 = v[j] * cc[j] + other * sn[j];
;                             v[j] = fq == 0 ? r0 : (fq == 1 ? r1 : v[j]);
;                         }
;                     }
.LBB0_579:
	v_bitop3_b32 v120, s74, v180, v172 bitop3:0xc8
	v_lshlrev_b32_e32 v152, 6, v120
	v_lshl_add_u64 v[104:105], s[70:71], 0, v[152:153]
	s_andn2_b64 vcc, exec, s[58:59]
	v_lshl_add_u64 v[114:115], v[104:105], 0, s[34:35]
	s_cbranch_vccnz .LBB0_629
	global_load_dwordx4 v[108:111], v[114:115], off offset:16
	global_load_dwordx4 v[0:3], v[114:115], off
	global_load_dwordx4 v[104:107], v[114:115], off offset:48
	global_load_dwordx4 v[4:7], v[114:115], off offset:32
	v_cmp_eq_u32_e32 vcc, 0, v168
	v_and_b32_e32 v237, 1, v168
	v_bfrev_b32_e32 v239, 1
	v_cmp_eq_u32_e64 s[52:53], 1, v237
	v_cmp_gt_u32_e64 s[58:59], 2, v168
	v_cndmask_b32_e32 v238, 0, v239, vcc
	v_mov_b32_e32 v248, v8
	v_mov_b32_e32 v252, v8
	v_mov_b32_e32 v249, v9
	v_mov_b32_e32 v253, v9
	v_mov_b32_e32 v250, v10
	v_mov_b32_e32 v254, v10
	v_mov_b32_e32 v251, v11
	v_mov_b32_e32 v255, v11
	v_permlane16_swap_b32_e32 v248, v252
	v_permlane16_swap_b32_e32 v249, v253
	v_permlane16_swap_b32_e32 v250, v254
	v_permlane16_swap_b32_e32 v251, v255
	s_nop 1
	v_cndmask_b32_e64 v248, v252, v248, s[52:53]
	v_cndmask_b32_e64 v249, v253, v249, s[52:53]
	v_cndmask_b32_e64 v250, v254, v250, s[52:53]
	v_cndmask_b32_e64 v251, v255, v251, s[52:53]
	s_waitcnt vmcnt(0)
	v_mul_f32_e32 v252, v8, v0
	v_xor_b32_e32 v237, v238, v1
	v_mul_f32_e32 v248, v248, v237
	v_add_f32_e32 v248, v252, v248
	v_cndmask_b32_e64 v8, v8, v248, s[58:59]
	v_mul_f32_e32 v253, v9, v2
	v_xor_b32_e32 v237, v238, v3
	v_mul_f32_e32 v249, v249, v237
	v_add_f32_e32 v249, v253, v249
	v_cndmask_b32_e64 v9, v9, v249, s[58:59]
	v_mul_f32_e32 v254, v10, v108
	v_xor_b32_e32 v237, v238, v109
	v_mul_f32_e32 v250, v250, v237
	v_add_f32_e32 v250, v254, v250
	v_cndmask_b32_e64 v10, v10, v250, s[58:59]
	v_mul_f32_e32 v255, v11, v110
	v_xor_b32_e32 v237, v238, v111
	v_mul_f32_e32 v251, v251, v237
	v_add_f32_e32 v251, v255, v251
	v_cndmask_b32_e64 v11, v11, v251, s[58:59]
	v_mov_b32_e32 v248, v12
	v_mov_b32_e32 v252, v12
	v_mov_b32_e32 v249, v13
	v_mov_b32_e32 v253, v13
	v_mov_b32_e32 v250, v14
	v_mov_b32_e32 v254, v14
	v_mov_b32_e32 v251, v15
	v_mov_b32_e32 v255, v15
	v_permlane16_swap_b32_e32 v248, v252
	v_permlane16_swap_b32_e32 v249, v253
	v_permlane16_swap_b32_e32 v250, v254
	v_permlane16_swap_b32_e32 v251, v255
	s_nop 1
	v_cndmask_b32_e64 v248, v252, v248, s[52:53]
	v_cndmask_b32_e64 v249, v253, v249, s[52:53]
	v_cndmask_b32_e64 v250, v254, v250, s[52:53]
	v_cndmask_b32_e64 v251, v255, v251, s[52:53]
	v_mul_f32_e32 v252, v12, v4
	v_xor_b32_e32 v237, v238, v5
	v_mul_f32_e32 v248, v248, v237
	v_add_f32_e32 v248, v252, v248
	v_cndmask_b32_e64 v12, v12, v248, s[58:59]
	v_mul_f32_e32 v253, v13, v6
	v_xor_b32_e32 v237, v238, v7
	v_mul_f32_e32 v249, v249, v237
	v_add_f32_e32 v249, v253, v249
	v_cndmask_b32_e64 v13, v13, v249, s[58:59]
	v_mul_f32_e32 v254, v14, v104
	v_xor_b32_e32 v237, v238, v105
	v_mul_f32_e32 v250, v250, v237
	v_add_f32_e32 v250, v254, v250
	v_cndmask_b32_e64 v14, v14, v250, s[58:59]
	v_mul_f32_e32 v255, v15, v106
	v_xor_b32_e32 v237, v238, v107
	v_mul_f32_e32 v251, v251, v237
	v_add_f32_e32 v251, v255, v251
	v_cndmask_b32_e64 v15, v15, v251, s[58:59]
	v_mov_b64_e32 v[0:1], v[8:9]
	v_mov_b64_e32 v[2:3], v[10:11]
	v_mov_b64_e32 v[4:5], v[12:13]
	v_mov_b64_e32 v[6:7], v[14:15]

;     DI void operator()(const pg8::f32x4 (&acc)[2][2][4][2], const pg8::Unit& u, int wr, int wc, int fr, int fq) const {
;     ...
;                     for (int j = 0; j < 4; ++j) { v[j] = acc[ai][bj][m][0][j] * rsq; v[4 + j] = acc[ai][bj][m][1][j] * rsq; }
;                     if (do_rope) {
;                         const f32x4* cs = (const f32x4*)(rope + (size_t)pos * 16);
;                         const f32x4 c01 = cs[0], c23 = cs[1], c45 = cs[2], c67 = cs[3];
;                         const float cc[8] = {c01.x, c01.z, c23.x, c23.z, c45.x, c45.z, c67.x, c67.z};
;                         const float sn[8] = {c01.y, c01.w, c23.y, c23.w, c45.y, c45.w, c67.y, c67.w};
; #pragma unroll
;                         for (int j = 0; j < 8; ++j) {
;                             const float other = __shfl_xor(v[j], 16);
;                             const float r0 = v[j] * cc[j] - other * sn[j], r1 = v[j] * cc[j] + other * sn[j];
;                             v[j] = fq == 0 ? r0 : (fq == 1 ? r1 : v[j]);
;                         }
;                     }
.LBB0_670:
	global_load_dwordx4 v[100:103], v[114:115], off offset:16
	global_load_dwordx4 v[0:3], v[114:115], off
	global_load_dwordx4 v[96:99], v[114:115], off offset:48
	global_load_dwordx4 v[4:7], v[114:115], off offset:32
	v_cmp_eq_u32_e32 vcc, 0, v168
	v_and_b32_e32 v237, 1, v168
	v_bfrev_b32_e32 v239, 1
	v_cmp_eq_u32_e64 s[52:53], 1, v237
	v_cmp_gt_u32_e64 s[58:59], 2, v168
	v_cndmask_b32_e32 v238, 0, v239, vcc
	v_mov_b32_e32 v248, v8
	v_mov_b32_e32 v252, v8
	v_mov_b32_e32 v249, v9
	v_mov_b32_e32 v253, v9
	v_mov_b32_e32 v250, v10
	v_mov_b32_e32 v254, v10
	v_mov_b32_e32 v251, v11
	v_mov_b32_e32 v255, v11
	v_permlane16_swap_b32_e32 v248, v252
	v_permlane16_swap_b32_e32 v249, v253
	v_permlane16_swap_b32_e32 v250, v254
	v_permlane16_swap_b32_e32 v251, v255
	s_nop 1
	v_cndmask_b32_e64 v248, v252, v248, s[52:53]
	v_cndmask_b32_e64 v249, v253, v249, s[52:53]
	v_cndmask_b32_e64 v250, v254, v250, s[52:53]
	v_cndmask_b32_e64 v251, v255, v251, s[52:53]
	s_waitcnt vmcnt(0)
	v_mul_f32_e32 v252, v8, v0
	v_xor_b32_e32 v237, v238, v1
	v_mul_f32_e32 v248, v248, v237
	v_add_f32_e32 v248, v252, v248
	v_cndmask_b32_e64 v8, v8, v248, s[58:59]
	v_mul_f32_e32 v253, v9, v2
	v_xor_b32_e32 v237, v238, v3
	v_mul_f32_e32 v249, v249, v237
	v_add_f32_e32 v249, v253, v249
	v_cndmask_b32_e64 v9, v9, v249, s[58:59]
	v_mul_f32_e32 v254, v10, v100
	v_xor_b32_e32 v237, v238, v101
	v_mul_f32_e32 v250, v250, v237
	v_add_f32_e32 v250, v254, v250
	v_cndmask_b32_e64 v10, v10, v250, s[58:59]
	v_mul_f32_e32 v255, v11, v102
	v_xor_b32_e32 v237, v238, v103
	v_mul_f32_e32 v251, v251, v237
	v_add_f32_e32 v251, v255, v251
	v_cndmask_b32_e64 v11, v11, v251, s[58:59]
	v_mov_b32_e32 v248, v12
	v_mov_b32_e32 v252, v12
	v_mov_b32_e32 v249, v13
	v_mov_b32_e32 v253, v13
	v_mov_b32_e32 v250, v14
	v_mov_b32_e32 v254, v14
	v_mov_b32_e32 v251, v15
	v_mov_b32_e32 v255, v15
	v_permlane16_swap_b32_e32 v248, v252
	v_permlane16_swap_b32_e32 v249, v253
	v_permlane16_swap_b32_e32 v250, v254
	v_permlane16_swap_b32_e32 v251, v255
	s_nop 1
	v_cndmask_b32_e64 v248, v252, v248, s[52:53]
	v_cndmask_b32_e64 v249, v253, v249, s[52:53]
	v_cndmask_b32_e64 v250, v254, v250, s[52:53]
	v_cndmask_b32_e64 v251, v255, v251, s[52:53]
	v_mul_f32_e32 v252, v12, v4
	v_xor_b32_e32 v237, v238, v5
	v_mul_f32_e32 v248, v248, v237
	v_add_f32_e32 v248, v252, v248
	v_cndmask_b32_e64 v12, v12, v248, s[58:59]
	v_mul_f32_e32 v253, v13, v6
	v_xor_b32_e32 v237, v238, v7
	v_mul_f32_e32 v249, v249, v237
	v_add_f32_e32 v249, v253, v249
	v_cndmask_b32_e64 v13, v13, v249, s[58:59]
	v_mul_f32_e32 v254, v14, v96
	v_xor_b32_e32 v237, v238, v97
	v_mul_f32_e32 v250, v250, v237
	v_add_f32_e32 v250, v254, v250
	v_cndmask_b32_e64 v14, v14, v250, s[58:59]
	v_mul_f32_e32 v255, v15, v98
	v_xor_b32_e32 v237, v238, v99
	v_mul_f32_e32 v251, v251, v237
	v_add_f32_e32 v251, v255, v251
	v_cndmask_b32_e64 v15, v15, v251, s[58:59]
	v_mov_b64_e32 v[0:1], v[8:9]
	v_mov_b64_e32 v[2:3], v[10:11]
	v_mov_b64_e32 v[4:5], v[12:13]
	v_mov_b64_e32 v[6:7], v[14:15]
	s_and_b64 vcc, exec, s[8:9]
	s_mov_b64 s[58:59], -1
	s_cbranch_vccz .LBB0_662

;     DI void operator()(const pg8::f32x4 (&acc)[2][2][4][2], const pg8::Unit& u, int wr, int wc, int fr, int fq) const {
;     ...
;                 const int pos = 16 + (tok & 4095), b = tok >> 12, s = tok & 4095;
; #pragma unroll
;                 for (int bj = 0; bj < 2; ++bj) {
;                     const int nb = nc0 + bj * 128 + wc * 32 + 8 * fq;
;                     float v[8];
; #pragma unroll
;                     for (int j = 0; j < 4; ++j) { v[j] = acc[ai][bj][m][0][j] * rsq; v[4 + j] = acc[ai][bj][m][1][j] * rsq; }
;                     if (do_rope) {
;                         const f32x4* cs = (const f32x4*)(rope + (size_t)pos * 16);
;                         const f32x4 c01 = cs[0], c23 = cs[1], c45 = cs[2], c67 = cs[3];
;                         const float cc[8] = {c01.x, c01.z, c23.x, c23.z, c45.x, c45.z, c67.x, c67.z};
;                         const float sn[8] = {c01.y, c01.w, c23.y, c23.w, c45.y, c45.w, c67.y, c67.w};
; #pragma unroll
;                         for (int j = 0; j < 8; ++j) {
;                             const float other = __shfl_xor(v[j], 16);
;                             const float r0 = v[j] * cc[j] - other * sn[j], r1 = v[j] * cc[j] + other * sn[j];
;                             v[j] = fq == 0 ? r0 : (fq == 1 ? r1 : v[j]);
;                         }
;                     }
.LBB0_723:
	v_bitop3_b32 v104, s74, v181, v173 bitop3:0xc8
	v_lshlrev_b32_e32 v152, 6, v104
	v_lshl_add_u64 v[88:89], s[70:71], 0, v[152:153]
	s_andn2_b64 vcc, exec, s[58:59]
	v_lshl_add_u64 v[98:99], v[88:89], 0, s[34:35]
	s_cbranch_vccnz .LBB0_773
	global_load_dwordx4 v[92:95], v[98:99], off offset:16
	global_load_dwordx4 v[0:3], v[98:99], off
	global_load_dwordx4 v[88:91], v[98:99], off offset:48
	global_load_dwordx4 v[4:7], v[98:99], off offset:32
	v_cmp_eq_u32_e32 vcc, 0, v168
	v_and_b32_e32 v237, 1, v168
	v_bfrev_b32_e32 v239, 1
	v_cmp_eq_u32_e64 s[52:53], 1, v237
	v_cmp_gt_u32_e64 s[58:59], 2, v168
	v_cndmask_b32_e32 v238, 0, v239, vcc
	v_mov_b32_e32 v248, v8
	v_mov_b32_e32 v252, v8
	v_mov_b32_e32 v249, v9
	v_mov_b32_e32 v253, v9
	v_mov_b32_e32 v250, v10
	v_mov_b32_e32 v254, v10
	v_mov_b32_e32 v251, v11
	v_mov_b32_e32 v255, v11
	v_permlane16_swap_b32_e32 v248, v252
	v_permlane16_swap_b32_e32 v249, v253
	v_permlane16_swap_b32_e32 v250, v254
	v_permlane16_swap_b32_e32 v251, v255
	s_nop 1
	v_cndmask_b32_e64 v248, v252, v248, s[52:53]
	v_cndmask_b32_e64 v249, v253, v249, s[52:53]
	v_cndmask_b32_e64 v250, v254, v250, s[52:53]
	v_cndmask_b32_e64 v251, v255, v251, s[52:53]
	s_waitcnt vmcnt(0)
	v_mul_f32_e32 v252, v8, v0
	v_xor_b32_e32 v237, v238, v1
	v_mul_f32_e32 v248, v248, v237
	v_add_f32_e32 v248, v252, v248
	v_cndmask_b32_e64 v8, v8, v248, s[58:59]
	v_mul_f32_e32 v253, v9, v2
	v_xor_b32_e32 v237, v238, v3
	v_mul_f32_e32 v249, v249, v237
	v_add_f32_e32 v249, v253, v249
	v_cndmask_b32_e64 v9, v9, v249, s[58:59]
	v_mul_f32_e32 v254, v10, v92
	v_xor_b32_e32 v237, v238, v93
	v_mul_f32_e32 v250, v250, v237
	v_add_f32_e32 v250, v254, v250
	v_cndmask_b32_e64 v10, v10, v250, s[58:59]
	v_mul_f32_e32 v255, v11, v94
	v_xor_b32_e32 v237, v238, v95
	v_mul_f32_e32 v251, v251, v237
	v_add_f32_e32 v251, v255, v251
	v_cndmask_b32_e64 v11, v11, v251, s[58:59]
	v_mov_b32_e32 v248, v12
	v_mov_b32_e32 v252, v12
	v_mov_b32_e32 v249, v13
	v_mov_b32_e32 v253, v13
	v_mov_b32_e32 v250, v14
	v_mov_b32_e32 v254, v14
	v_mov_b32_e32 v251, v15
	v_mov_b32_e32 v255, v15
	v_permlane16_swap_b32_e32 v248, v252
	v_permlane16_swap_b32_e32 v249, v253
	v_permlane16_swap_b32_e32 v250, v254
	v_permlane16_swap_b32_e32 v251, v255
	s_nop 1
	v_cndmask_b32_e64 v248, v252, v248, s[52:53]
	v_cndmask_b32_e64 v249, v253, v249, s[52:53]
	v_cndmask_b32_e64 v250, v254, v250, s[52:53]
	v_cndmask_b32_e64 v251, v255, v251, s[52:53]
	v_mul_f32_e32 v252, v12, v4
	v_xor_b32_e32 v237, v238, v5
	v_mul_f32_e32 v248, v248, v237
	v_add_f32_e32 v248, v252, v248
	v_cndmask_b32_e64 v12, v12, v248, s[58:59]
	v_mul_f32_e32 v253, v13, v6
	v_xor_b32_e32 v237, v238, v7
	v_mul_f32_e32 v249, v249, v237
	v_add_f32_e32 v249, v253, v249
	v_cndmask_b32_e64 v13, v13, v249, s[58:59]
	v_mul_f32_e32 v254, v14, v88
	v_xor_b32_e32 v237, v238, v89
	v_mul_f32_e32 v250, v250, v237
	v_add_f32_e32 v250, v254, v250
	v_cndmask_b32_e64 v14, v14, v250, s[58:59]
	v_mul_f32_e32 v255, v15, v90
	v_xor_b32_e32 v237, v238, v91
	v_mul_f32_e32 v251, v251, v237
	v_add_f32_e32 v251, v255, v251
	v_cndmask_b32_e64 v15, v15, v251, s[58:59]
	v_mov_b64_e32 v[0:1], v[8:9]
	v_mov_b64_e32 v[2:3], v[10:11]
	v_mov_b64_e32 v[4:5], v[12:13]
	v_mov_b64_e32 v[6:7], v[14:15]

;     DI void operator()(const pg8::f32x4 (&acc)[2][2][4][2], const pg8::Unit& u, int wr, int wc, int fr, int fq) const {
;     ...
;                     for (int j = 0; j < 4; ++j) { v[j] = acc[ai][bj][m][0][j] * rsq; v[4 + j] = acc[ai][bj][m][1][j] * rsq; }
;                     if (do_rope) {
;                         const f32x4* cs = (const f32x4*)(rope + (size_t)pos * 16);
;                         const f32x4 c01 = cs[0], c23 = cs[1], c45 = cs[2], c67 = cs[3];
;                         const float cc[8] = {c01.x, c01.z, c23.x, c23.z, c45.x, c45.z, c67.x, c67.z};
;                         const float sn[8] = {c01.y, c01.w, c23.y, c23.w, c45.y, c45.w, c67.y, c67.w};
; #pragma unroll
;                         for (int j = 0; j < 8; ++j) {
;                             const float other = __shfl_xor(v[j], 16);
;                             const float r0 = v[j] * cc[j] - other * sn[j], r1 = v[j] * cc[j] + other * sn[j];
;                             v[j] = fq == 0 ? r0 : (fq == 1 ? r1 : v[j]);
;                         }
;                     }
.LBB0_814:
	global_load_dwordx4 v[84:87], v[98:99], off offset:16
	global_load_dwordx4 v[0:3], v[98:99], off
	global_load_dwordx4 v[80:83], v[98:99], off offset:48
	global_load_dwordx4 v[4:7], v[98:99], off offset:32
	v_cmp_eq_u32_e32 vcc, 0, v168
	v_and_b32_e32 v237, 1, v168
	v_bfrev_b32_e32 v239, 1
	v_cmp_eq_u32_e64 s[52:53], 1, v237
	v_cmp_gt_u32_e64 s[58:59], 2, v168
	v_cndmask_b32_e32 v238, 0, v239, vcc
	v_mov_b32_e32 v248, v8
	v_mov_b32_e32 v252, v8
	v_mov_b32_e32 v249, v9
	v_mov_b32_e32 v253, v9
	v_mov_b32_e32 v250, v10
	v_mov_b32_e32 v254, v10
	v_mov_b32_e32 v251, v11
	v_mov_b32_e32 v255, v11
	v_permlane16_swap_b32_e32 v248, v252
	v_permlane16_swap_b32_e32 v249, v253
	v_permlane16_swap_b32_e32 v250, v254
	v_permlane16_swap_b32_e32 v251, v255
	s_nop 1
	v_cndmask_b32_e64 v248, v252, v248, s[52:53]
	v_cndmask_b32_e64 v249, v253, v249, s[52:53]
	v_cndmask_b32_e64 v250, v254, v250, s[52:53]
	v_cndmask_b32_e64 v251, v255, v251, s[52:53]
	s_waitcnt vmcnt(0)
	v_mul_f32_e32 v252, v8, v0
	v_xor_b32_e32 v237, v238, v1
	v_mul_f32_e32 v248, v248, v237
	v_add_f32_e32 v248, v252, v248
	v_cndmask_b32_e64 v8, v8, v248, s[58:59]
	v_mul_f32_e32 v253, v9, v2
	v_xor_b32_e32 v237, v238, v3
	v_mul_f32_e32 v249, v249, v237
	v_add_f32_e32 v249, v253, v249
	v_cndmask_b32_e64 v9, v9, v249, s[58:59]
	v_mul_f32_e32 v254, v10, v84
	v_xor_b32_e32 v237, v238, v85
	v_mul_f32_e32 v250, v250, v237
	v_add_f32_e32 v250, v254, v250
	v_cndmask_b32_e64 v10, v10, v250, s[58:59]
	v_mul_f32_e32 v255, v11, v86
	v_xor_b32_e32 v237, v238, v87
	v_mul_f32_e32 v251, v251, v237
	v_add_f32_e32 v251, v255, v251
	v_cndmask_b32_e64 v11, v11, v251, s[58:59]
	v_mov_b32_e32 v248, v12
	v_mov_b32_e32 v252, v12
	v_mov_b32_e32 v249, v13
	v_mov_b32_e32 v253, v13
	v_mov_b32_e32 v250, v14
	v_mov_b32_e32 v254, v14
	v_mov_b32_e32 v251, v15
	v_mov_b32_e32 v255, v15
	v_permlane16_swap_b32_e32 v248, v252
	v_permlane16_swap_b32_e32 v249, v253
	v_permlane16_swap_b32_e32 v250, v254
	v_permlane16_swap_b32_e32 v251, v255
	s_nop 1
	v_cndmask_b32_e64 v248, v252, v248, s[52:53]
	v_cndmask_b32_e64 v249, v253, v249, s[52:53]
	v_cndmask_b32_e64 v250, v254, v250, s[52:53]
	v_cndmask_b32_e64 v251, v255, v251, s[52:53]
	v_mul_f32_e32 v252, v12, v4
	v_xor_b32_e32 v237, v238, v5
	v_mul_f32_e32 v248, v248, v237
	v_add_f32_e32 v248, v252, v248
	v_cndmask_b32_e64 v12, v12, v248, s[58:59]
	v_mul_f32_e32 v253, v13, v6
	v_xor_b32_e32 v237, v238, v7
	v_mul_f32_e32 v249, v249, v237
	v_add_f32_e32 v249, v253, v249
	v_cndmask_b32_e64 v13, v13, v249, s[58:59]
	v_mul_f32_e32 v254, v14, v80
	v_xor_b32_e32 v237, v238, v81
	v_mul_f32_e32 v250, v250, v237
	v_add_f32_e32 v250, v254, v250
	v_cndmask_b32_e64 v14, v14, v250, s[58:59]
	v_mul_f32_e32 v255, v15, v82
	v_xor_b32_e32 v237, v238, v83
	v_mul_f32_e32 v251, v251, v237
	v_add_f32_e32 v251, v255, v251
	v_cndmask_b32_e64 v15, v15, v251, s[58:59]
	v_mov_b64_e32 v[0:1], v[8:9]
	v_mov_b64_e32 v[2:3], v[10:11]
	v_mov_b64_e32 v[4:5], v[12:13]
	v_mov_b64_e32 v[6:7], v[14:15]
	s_and_b64 vcc, exec, s[8:9]
	s_mov_b64 s[58:59], -1
	s_cbranch_vccz .LBB0_806

;     DI void operator()(const pg8::f32x4 (&acc)[2][2][4][2], const pg8::Unit& u, int wr, int wc, int fr, int fq) const {
;     ...
;                 const int pos = 16 + (tok & 4095), b = tok >> 12, s = tok & 4095;
; #pragma unroll
;                 for (int bj = 0; bj < 2; ++bj) {
;                     const int nb = nc0 + bj * 128 + wc * 32 + 8 * fq;
;                     float v[8];
; #pragma unroll
;                     for (int j = 0; j < 4; ++j) { v[j] = acc[ai][bj][m][0][j] * rsq; v[4 + j] = acc[ai][bj][m][1][j] * rsq; }
;                     if (do_rope) {
;                         const f32x4* cs = (const f32x4*)(rope + (size_t)pos * 16);
;                         const f32x4 c01 = cs[0], c23 = cs[1], c45 = cs[2], c67 = cs[3];
;                         const float cc[8] = {c01.x, c01.z, c23.x, c23.z, c45.x, c45.z, c67.x, c67.z};
;                         const float sn[8] = {c01.y, c01.w, c23.y, c23.w, c45.y, c45.w, c67.y, c67.w};
; #pragma unroll
;                         for (int j = 0; j < 8; ++j) {
;                             const float other = __shfl_xor(v[j], 16);
;                             const float r0 = v[j] * cc[j] - other * sn[j], r1 = v[j] * cc[j] + other * sn[j];
;                             v[j] = fq == 0 ? r0 : (fq == 1 ? r1 : v[j]);
;                         }
;                     }
.LBB0_867:
	v_bitop3_b32 v88, s74, v177, v167 bitop3:0xc8
	v_lshlrev_b32_e32 v152, 6, v88
	v_lshl_add_u64 v[72:73], s[70:71], 0, v[152:153]
	s_andn2_b64 vcc, exec, s[58:59]
	v_lshl_add_u64 v[82:83], v[72:73], 0, s[34:35]
	s_cbranch_vccnz .LBB0_917
	global_load_dwordx4 v[76:79], v[82:83], off offset:16
	global_load_dwordx4 v[0:3], v[82:83], off
	global_load_dwordx4 v[72:75], v[82:83], off offset:48
	global_load_dwordx4 v[4:7], v[82:83], off offset:32
	v_cmp_eq_u32_e32 vcc, 0, v168
	v_and_b32_e32 v237, 1, v168
	v_bfrev_b32_e32 v239, 1
	v_cmp_eq_u32_e64 s[52:53], 1, v237
	v_cmp_gt_u32_e64 s[58:59], 2, v168
	v_cndmask_b32_e32 v238, 0, v239, vcc
	v_mov_b32_e32 v248, v8
	v_mov_b32_e32 v252, v8
	v_mov_b32_e32 v249, v9
	v_mov_b32_e32 v253, v9
	v_mov_b32_e32 v250, v10
	v_mov_b32_e32 v254, v10
	v_mov_b32_e32 v251, v11
	v_mov_b32_e32 v255, v11
	v_permlane16_swap_b32_e32 v248, v252
	v_permlane16_swap_b32_e32 v249, v253
	v_permlane16_swap_b32_e32 v250, v254
	v_permlane16_swap_b32_e32 v251, v255
	s_nop 1
	v_cndmask_b32_e64 v248, v252, v248, s[52:53]
	v_cndmask_b32_e64 v249, v253, v249, s[52:53]
	v_cndmask_b32_e64 v250, v254, v250, s[52:53]
	v_cndmask_b32_e64 v251, v255, v251, s[52:53]
	s_waitcnt vmcnt(0)
	v_mul_f32_e32 v252, v8, v0
	v_xor_b32_e32 v237, v238, v1
	v_mul_f32_e32 v248, v248, v237
	v_add_f32_e32 v248, v252, v248
	v_cndmask_b32_e64 v8, v8, v248, s[58:59]
	v_mul_f32_e32 v253, v9, v2
	v_xor_b32_e32 v237, v238, v3
	v_mul_f32_e32 v249, v249, v237
	v_add_f32_e32 v249, v253, v249
	v_cndmask_b32_e64 v9, v9, v249, s[58:59]
	v_mul_f32_e32 v254, v10, v76
	v_xor_b32_e32 v237, v238, v77
	v_mul_f32_e32 v250, v250, v237
	v_add_f32_e32 v250, v254, v250
	v_cndmask_b32_e64 v10, v10, v250, s[58:59]
	v_mul_f32_e32 v255, v11, v78
	v_xor_b32_e32 v237, v238, v79
	v_mul_f32_e32 v251, v251, v237
	v_add_f32_e32 v251, v255, v251
	v_cndmask_b32_e64 v11, v11, v251, s[58:59]
	v_mov_b32_e32 v248, v12
	v_mov_b32_e32 v252, v12
	v_mov_b32_e32 v249, v13
	v_mov_b32_e32 v253, v13
	v_mov_b32_e32 v250, v14
	v_mov_b32_e32 v254, v14
	v_mov_b32_e32 v251, v15
	v_mov_b32_e32 v255, v15
	v_permlane16_swap_b32_e32 v248, v252
	v_permlane16_swap_b32_e32 v249, v253
	v_permlane16_swap_b32_e32 v250, v254
	v_permlane16_swap_b32_e32 v251, v255
	s_nop 1
	v_cndmask_b32_e64 v248, v252, v248, s[52:53]
	v_cndmask_b32_e64 v249, v253, v249, s[52:53]
	v_cndmask_b32_e64 v250, v254, v250, s[52:53]
	v_cndmask_b32_e64 v251, v255, v251, s[52:53]
	v_mul_f32_e32 v252, v12, v4
	v_xor_b32_e32 v237, v238, v5
	v_mul_f32_e32 v248, v248, v237
	v_add_f32_e32 v248, v252, v248
	v_cndmask_b32_e64 v12, v12, v248, s[58:59]
	v_mul_f32_e32 v253, v13, v6
	v_xor_b32_e32 v237, v238, v7
	v_mul_f32_e32 v249, v249, v237
	v_add_f32_e32 v249, v253, v249
	v_cndmask_b32_e64 v13, v13, v249, s[58:59]
	v_mul_f32_e32 v254, v14, v72
	v_xor_b32_e32 v237, v238, v73
	v_mul_f32_e32 v250, v250, v237
	v_add_f32_e32 v250, v254, v250
	v_cndmask_b32_e64 v14, v14, v250, s[58:59]
	v_mul_f32_e32 v255, v15, v74
	v_xor_b32_e32 v237, v238, v75
	v_mul_f32_e32 v251, v251, v237
	v_add_f32_e32 v251, v255, v251
	v_cndmask_b32_e64 v15, v15, v251, s[58:59]
	v_mov_b64_e32 v[0:1], v[8:9]
	v_mov_b64_e32 v[2:3], v[10:11]
	v_mov_b64_e32 v[4:5], v[12:13]
	v_mov_b64_e32 v[6:7], v[14:15]

;     DI void operator()(const pg8::f32x4 (&acc)[2][2][4][2], const pg8::Unit& u, int wr, int wc, int fr, int fq) const {
;     ...
;                     for (int j = 0; j < 4; ++j) { v[j] = acc[ai][bj][m][0][j] * rsq; v[4 + j] = acc[ai][bj][m][1][j] * rsq; }
;                     if (do_rope) {
;                         const f32x4* cs = (const f32x4*)(rope + (size_t)pos * 16);
;                         const f32x4 c01 = cs[0], c23 = cs[1], c45 = cs[2], c67 = cs[3];
;                         const float cc[8] = {c01.x, c01.z, c23.x, c23.z, c45.x, c45.z, c67.x, c67.z};
;                         const float sn[8] = {c01.y, c01.w, c23.y, c23.w, c45.y, c45.w, c67.y, c67.w};
; #pragma unroll
;                         for (int j = 0; j < 8; ++j) {
;                             const float other = __shfl_xor(v[j], 16);
;                             const float r0 = v[j] * cc[j] - other * sn[j], r1 = v[j] * cc[j] + other * sn[j];
;                             v[j] = fq == 0 ? r0 : (fq == 1 ? r1 : v[j]);
;                         }
;                     }
.LBB0_958:
	global_load_dwordx4 v[68:71], v[82:83], off offset:16
	global_load_dwordx4 v[0:3], v[82:83], off
	global_load_dwordx4 v[64:67], v[82:83], off offset:48
	global_load_dwordx4 v[4:7], v[82:83], off offset:32
	v_cmp_eq_u32_e32 vcc, 0, v168
	v_and_b32_e32 v237, 1, v168
	v_bfrev_b32_e32 v239, 1
	v_cmp_eq_u32_e64 s[52:53], 1, v237
	v_cmp_gt_u32_e64 s[58:59], 2, v168
	v_cndmask_b32_e32 v238, 0, v239, vcc
	v_mov_b32_e32 v248, v8
	v_mov_b32_e32 v252, v8
	v_mov_b32_e32 v249, v9
	v_mov_b32_e32 v253, v9
	v_mov_b32_e32 v250, v10
	v_mov_b32_e32 v254, v10
	v_mov_b32_e32 v251, v11
	v_mov_b32_e32 v255, v11
	v_permlane16_swap_b32_e32 v248, v252
	v_permlane16_swap_b32_e32 v249, v253
	v_permlane16_swap_b32_e32 v250, v254
	v_permlane16_swap_b32_e32 v251, v255
	s_nop 1
	v_cndmask_b32_e64 v248, v252, v248, s[52:53]
	v_cndmask_b32_e64 v249, v253, v249, s[52:53]
	v_cndmask_b32_e64 v250, v254, v250, s[52:53]
	v_cndmask_b32_e64 v251, v255, v251, s[52:53]
	s_waitcnt vmcnt(0)
	v_mul_f32_e32 v252, v8, v0
	v_xor_b32_e32 v237, v238, v1
	v_mul_f32_e32 v248, v248, v237
	v_add_f32_e32 v248, v252, v248
	v_cndmask_b32_e64 v8, v8, v248, s[58:59]
	v_mul_f32_e32 v253, v9, v2
	v_xor_b32_e32 v237, v238, v3
	v_mul_f32_e32 v249, v249, v237
	v_add_f32_e32 v249, v253, v249
	v_cndmask_b32_e64 v9, v9, v249, s[58:59]
	v_mul_f32_e32 v254, v10, v68
	v_xor_b32_e32 v237, v238, v69
	v_mul_f32_e32 v250, v250, v237
	v_add_f32_e32 v250, v254, v250
	v_cndmask_b32_e64 v10, v10, v250, s[58:59]
	v_mul_f32_e32 v255, v11, v70
	v_xor_b32_e32 v237, v238, v71
	v_mul_f32_e32 v251, v251, v237
	v_add_f32_e32 v251, v255, v251
	v_cndmask_b32_e64 v11, v11, v251, s[58:59]
	v_mov_b32_e32 v248, v12
	v_mov_b32_e32 v252, v12
	v_mov_b32_e32 v249, v13
	v_mov_b32_e32 v253, v13
	v_mov_b32_e32 v250, v14
	v_mov_b32_e32 v254, v14
	v_mov_b32_e32 v251, v15
	v_mov_b32_e32 v255, v15
	v_permlane16_swap_b32_e32 v248, v252
	v_permlane16_swap_b32_e32 v249, v253
	v_permlane16_swap_b32_e32 v250, v254
	v_permlane16_swap_b32_e32 v251, v255
	s_nop 1
	v_cndmask_b32_e64 v248, v252, v248, s[52:53]
	v_cndmask_b32_e64 v249, v253, v249, s[52:53]
	v_cndmask_b32_e64 v250, v254, v250, s[52:53]
	v_cndmask_b32_e64 v251, v255, v251, s[52:53]
	v_mul_f32_e32 v252, v12, v4
	v_xor_b32_e32 v237, v238, v5
	v_mul_f32_e32 v248, v248, v237
	v_add_f32_e32 v248, v252, v248
	v_cndmask_b32_e64 v12, v12, v248, s[58:59]
	v_mul_f32_e32 v253, v13, v6
	v_xor_b32_e32 v237, v238, v7
	v_mul_f32_e32 v249, v249, v237
	v_add_f32_e32 v249, v253, v249
	v_cndmask_b32_e64 v13, v13, v249, s[58:59]
	v_mul_f32_e32 v254, v14, v64
	v_xor_b32_e32 v237, v238, v65
	v_mul_f32_e32 v250, v250, v237
	v_add_f32_e32 v250, v254, v250
	v_cndmask_b32_e64 v14, v14, v250, s[58:59]
	v_mul_f32_e32 v255, v15, v66
	v_xor_b32_e32 v237, v238, v67
	v_mul_f32_e32 v251, v251, v237
	v_add_f32_e32 v251, v255, v251
	v_cndmask_b32_e64 v15, v15, v251, s[58:59]
	v_mov_b64_e32 v[0:1], v[8:9]
	v_mov_b64_e32 v[2:3], v[10:11]
	v_mov_b64_e32 v[4:5], v[12:13]
	v_mov_b64_e32 v[6:7], v[14:15]
	s_and_b64 vcc, exec, s[8:9]
	s_mov_b64 s[58:59], -1
	s_cbranch_vccz .LBB0_950

;     DI void operator()(const pg8::f32x4 (&acc)[2][2][4][2], const pg8::Unit& u, int wr, int wc, int fr, int fq) const {
;     ...
;                 const int pos = 16 + (tok & 4095), b = tok >> 12, s = tok & 4095;
; #pragma unroll
;                 for (int bj = 0; bj < 2; ++bj) {
;                     const int nb = nc0 + bj * 128 + wc * 32 + 8 * fq;
;                     float v[8];
; #pragma unroll
;                     for (int j = 0; j < 4; ++j) { v[j] = acc[ai][bj][m][0][j] * rsq; v[4 + j] = acc[ai][bj][m][1][j] * rsq; }
;                     if (do_rope) {
;                         const f32x4* cs = (const f32x4*)(rope + (size_t)pos * 16);
;                         const f32x4 c01 = cs[0], c23 = cs[1], c45 = cs[2], c67 = cs[3];
;                         const float cc[8] = {c01.x, c01.z, c23.x, c23.z, c45.x, c45.z, c67.x, c67.z};
;                         const float sn[8] = {c01.y, c01.w, c23.y, c23.w, c45.y, c45.w, c67.y, c67.w};
; #pragma unroll
;                         for (int j = 0; j < 8; ++j) {
;                             const float other = __shfl_xor(v[j], 16);
;                             const float r0 = v[j] * cc[j] - other * sn[j], r1 = v[j] * cc[j] + other * sn[j];
;                             v[j] = fq == 0 ? r0 : (fq == 1 ? r1 : v[j]);
;                         }
;                     }
.LBB0_1011:
	v_bitop3_b32 v72, s74, v179, v171 bitop3:0xc8
	v_lshlrev_b32_e32 v152, 6, v72
	v_lshl_add_u64 v[56:57], s[70:71], 0, v[152:153]
	s_andn2_b64 vcc, exec, s[58:59]
	v_lshl_add_u64 v[66:67], v[56:57], 0, s[34:35]
	s_cbranch_vccnz .LBB0_1061
	global_load_dwordx4 v[60:63], v[66:67], off offset:16
	global_load_dwordx4 v[0:3], v[66:67], off
	global_load_dwordx4 v[56:59], v[66:67], off offset:48
	global_load_dwordx4 v[4:7], v[66:67], off offset:32
	v_cmp_eq_u32_e32 vcc, 0, v168
	v_and_b32_e32 v237, 1, v168
	v_bfrev_b32_e32 v239, 1
	v_cmp_eq_u32_e64 s[52:53], 1, v237
	v_cmp_gt_u32_e64 s[58:59], 2, v168
	v_cndmask_b32_e32 v238, 0, v239, vcc
	v_mov_b32_e32 v248, v8
	v_mov_b32_e32 v252, v8
	v_mov_b32_e32 v249, v9
	v_mov_b32_e32 v253, v9
	v_mov_b32_e32 v250, v10
	v_mov_b32_e32 v254, v10
	v_mov_b32_e32 v251, v11
	v_mov_b32_e32 v255, v11
	v_permlane16_swap_b32_e32 v248, v252
	v_permlane16_swap_b32_e32 v249, v253
	v_permlane16_swap_b32_e32 v250, v254
	v_permlane16_swap_b32_e32 v251, v255
	s_nop 1
	v_cndmask_b32_e64 v248, v252, v248, s[52:53]
	v_cndmask_b32_e64 v249, v253, v249, s[52:53]
	v_cndmask_b32_e64 v250, v254, v250, s[52:53]
	v_cndmask_b32_e64 v251, v255, v251, s[52:53]
	s_waitcnt vmcnt(0)
	v_mul_f32_e32 v252, v8, v0
	v_xor_b32_e32 v237, v238, v1
	v_mul_f32_e32 v248, v248, v237
	v_add_f32_e32 v248, v252, v248
	v_cndmask_b32_e64 v8, v8, v248, s[58:59]
	v_mul_f32_e32 v253, v9, v2
	v_xor_b32_e32 v237, v238, v3
	v_mul_f32_e32 v249, v249, v237
	v_add_f32_e32 v249, v253, v249
	v_cndmask_b32_e64 v9, v9, v249, s[58:59]
	v_mul_f32_e32 v254, v10, v60
	v_xor_b32_e32 v237, v238, v61
	v_mul_f32_e32 v250, v250, v237
	v_add_f32_e32 v250, v254, v250
	v_cndmask_b32_e64 v10, v10, v250, s[58:59]
	v_mul_f32_e32 v255, v11, v62
	v_xor_b32_e32 v237, v238, v63
	v_mul_f32_e32 v251, v251, v237
	v_add_f32_e32 v251, v255, v251
	v_cndmask_b32_e64 v11, v11, v251, s[58:59]
	v_mov_b32_e32 v248, v12
	v_mov_b32_e32 v252, v12
	v_mov_b32_e32 v249, v13
	v_mov_b32_e32 v253, v13
	v_mov_b32_e32 v250, v14
	v_mov_b32_e32 v254, v14
	v_mov_b32_e32 v251, v15
	v_mov_b32_e32 v255, v15
	v_permlane16_swap_b32_e32 v248, v252
	v_permlane16_swap_b32_e32 v249, v253
	v_permlane16_swap_b32_e32 v250, v254
	v_permlane16_swap_b32_e32 v251, v255
	s_nop 1
	v_cndmask_b32_e64 v248, v252, v248, s[52:53]
	v_cndmask_b32_e64 v249, v253, v249, s[52:53]
	v_cndmask_b32_e64 v250, v254, v250, s[52:53]
	v_cndmask_b32_e64 v251, v255, v251, s[52:53]
	v_mul_f32_e32 v252, v12, v4
	v_xor_b32_e32 v237, v238, v5
	v_mul_f32_e32 v248, v248, v237
	v_add_f32_e32 v248, v252, v248
	v_cndmask_b32_e64 v12, v12, v248, s[58:59]
	v_mul_f32_e32 v253, v13, v6
	v_xor_b32_e32 v237, v238, v7
	v_mul_f32_e32 v249, v249, v237
	v_add_f32_e32 v249, v253, v249
	v_cndmask_b32_e64 v13, v13, v249, s[58:59]
	v_mul_f32_e32 v254, v14, v56
	v_xor_b32_e32 v237, v238, v57
	v_mul_f32_e32 v250, v250, v237
	v_add_f32_e32 v250, v254, v250
	v_cndmask_b32_e64 v14, v14, v250, s[58:59]
	v_mul_f32_e32 v255, v15, v58
	v_xor_b32_e32 v237, v238, v59
	v_mul_f32_e32 v251, v251, v237
	v_add_f32_e32 v251, v255, v251
	v_cndmask_b32_e64 v15, v15, v251, s[58:59]
	v_mov_b64_e32 v[0:1], v[8:9]
	v_mov_b64_e32 v[2:3], v[10:11]
	v_mov_b64_e32 v[4:5], v[12:13]
	v_mov_b64_e32 v[6:7], v[14:15]

;     DI void operator()(const pg8::f32x4 (&acc)[2][2][4][2], const pg8::Unit& u, int wr, int wc, int fr, int fq) const {
;     ...
;                     for (int j = 0; j < 4; ++j) { v[j] = acc[ai][bj][m][0][j] * rsq; v[4 + j] = acc[ai][bj][m][1][j] * rsq; }
;                     if (do_rope) {
;                         const f32x4* cs = (const f32x4*)(rope + (size_t)pos * 16);
;                         const f32x4 c01 = cs[0], c23 = cs[1], c45 = cs[2], c67 = cs[3];
;                         const float cc[8] = {c01.x, c01.z, c23.x, c23.z, c45.x, c45.z, c67.x, c67.z};
;                         const float sn[8] = {c01.y, c01.w, c23.y, c23.w, c45.y, c45.w, c67.y, c67.w};
; #pragma unroll
;                         for (int j = 0; j < 8; ++j) {
;                             const float other = __shfl_xor(v[j], 16);
;                             const float r0 = v[j] * cc[j] - other * sn[j], r1 = v[j] * cc[j] + other * sn[j];
;                             v[j] = fq == 0 ? r0 : (fq == 1 ? r1 : v[j]);
;                         }
;                     }
.LBB0_1102:
	global_load_dwordx4 v[52:55], v[66:67], off offset:16
	global_load_dwordx4 v[0:3], v[66:67], off
	global_load_dwordx4 v[48:51], v[66:67], off offset:48
	global_load_dwordx4 v[4:7], v[66:67], off offset:32
	v_cmp_eq_u32_e32 vcc, 0, v168
	v_and_b32_e32 v237, 1, v168
	v_bfrev_b32_e32 v239, 1
	v_cmp_eq_u32_e64 s[52:53], 1, v237
	v_cmp_gt_u32_e64 s[58:59], 2, v168
	v_cndmask_b32_e32 v238, 0, v239, vcc
	v_mov_b32_e32 v248, v8
	v_mov_b32_e32 v252, v8
	v_mov_b32_e32 v249, v9
	v_mov_b32_e32 v253, v9
	v_mov_b32_e32 v250, v10
	v_mov_b32_e32 v254, v10
	v_mov_b32_e32 v251, v11
	v_mov_b32_e32 v255, v11
	v_permlane16_swap_b32_e32 v248, v252
	v_permlane16_swap_b32_e32 v249, v253
	v_permlane16_swap_b32_e32 v250, v254
	v_permlane16_swap_b32_e32 v251, v255
	s_nop 1
	v_cndmask_b32_e64 v248, v252, v248, s[52:53]
	v_cndmask_b32_e64 v249, v253, v249, s[52:53]
	v_cndmask_b32_e64 v250, v254, v250, s[52:53]
	v_cndmask_b32_e64 v251, v255, v251, s[52:53]
	s_waitcnt vmcnt(0)
	v_mul_f32_e32 v252, v8, v0
	v_xor_b32_e32 v237, v238, v1
	v_mul_f32_e32 v248, v248, v237
	v_add_f32_e32 v248, v252, v248
	v_cndmask_b32_e64 v8, v8, v248, s[58:59]
	v_mul_f32_e32 v253, v9, v2
	v_xor_b32_e32 v237, v238, v3
	v_mul_f32_e32 v249, v249, v237
	v_add_f32_e32 v249, v253, v249
	v_cndmask_b32_e64 v9, v9, v249, s[58:59]
	v_mul_f32_e32 v254, v10, v52
	v_xor_b32_e32 v237, v238, v53
	v_mul_f32_e32 v250, v250, v237
	v_add_f32_e32 v250, v254, v250
	v_cndmask_b32_e64 v10, v10, v250, s[58:59]
	v_mul_f32_e32 v255, v11, v54
	v_xor_b32_e32 v237, v238, v55
	v_mul_f32_e32 v251, v251, v237
	v_add_f32_e32 v251, v255, v251
	v_cndmask_b32_e64 v11, v11, v251, s[58:59]
	v_mov_b32_e32 v248, v12
	v_mov_b32_e32 v252, v12
	v_mov_b32_e32 v249, v13
	v_mov_b32_e32 v253, v13
	v_mov_b32_e32 v250, v14
	v_mov_b32_e32 v254, v14
	v_mov_b32_e32 v251, v15
	v_mov_b32_e32 v255, v15
	v_permlane16_swap_b32_e32 v248, v252
	v_permlane16_swap_b32_e32 v249, v253
	v_permlane16_swap_b32_e32 v250, v254
	v_permlane16_swap_b32_e32 v251, v255
	s_nop 1
	v_cndmask_b32_e64 v248, v252, v248, s[52:53]
	v_cndmask_b32_e64 v249, v253, v249, s[52:53]
	v_cndmask_b32_e64 v250, v254, v250, s[52:53]
	v_cndmask_b32_e64 v251, v255, v251, s[52:53]
	v_mul_f32_e32 v252, v12, v4
	v_xor_b32_e32 v237, v238, v5
	v_mul_f32_e32 v248, v248, v237
	v_add_f32_e32 v248, v252, v248
	v_cndmask_b32_e64 v12, v12, v248, s[58:59]
	v_mul_f32_e32 v253, v13, v6
	v_xor_b32_e32 v237, v238, v7
	v_mul_f32_e32 v249, v249, v237
	v_add_f32_e32 v249, v253, v249
	v_cndmask_b32_e64 v13, v13, v249, s[58:59]
	v_mul_f32_e32 v254, v14, v48
	v_xor_b32_e32 v237, v238, v49
	v_mul_f32_e32 v250, v250, v237
	v_add_f32_e32 v250, v254, v250
	v_cndmask_b32_e64 v14, v14, v250, s[58:59]
	v_mul_f32_e32 v255, v15, v50
	v_xor_b32_e32 v237, v238, v51
	v_mul_f32_e32 v251, v251, v237
	v_add_f32_e32 v251, v255, v251
	v_cndmask_b32_e64 v15, v15, v251, s[58:59]
	v_mov_b64_e32 v[0:1], v[8:9]
	v_mov_b64_e32 v[2:3], v[10:11]
	v_mov_b64_e32 v[4:5], v[12:13]
	v_mov_b64_e32 v[6:7], v[14:15]
	s_and_b64 vcc, exec, s[8:9]
	s_mov_b64 s[58:59], -1
	s_cbranch_vccz .LBB0_1094

;     DI void operator()(const pg8::f32x4 (&acc)[2][2][4][2], const pg8::Unit& u, int wr, int wc, int fr, int fq) const {
;     ...
;                 const int pos = 16 + (tok & 4095), b = tok >> 12, s = tok & 4095;
; #pragma unroll
;                 for (int bj = 0; bj < 2; ++bj) {
;                     const int nb = nc0 + bj * 128 + wc * 32 + 8 * fq;
;                     float v[8];
; #pragma unroll
;                     for (int j = 0; j < 4; ++j) { v[j] = acc[ai][bj][m][0][j] * rsq; v[4 + j] = acc[ai][bj][m][1][j] * rsq; }
;                     if (do_rope) {
;                         const f32x4* cs = (const f32x4*)(rope + (size_t)pos * 16);
;                         const f32x4 c01 = cs[0], c23 = cs[1], c45 = cs[2], c67 = cs[3];
;                         const float cc[8] = {c01.x, c01.z, c23.x, c23.z, c45.x, c45.z, c67.x, c67.z};
;                         const float sn[8] = {c01.y, c01.w, c23.y, c23.w, c45.y, c45.w, c67.y, c67.w};
; #pragma unroll
;                         for (int j = 0; j < 8; ++j) {
;                             const float other = __shfl_xor(v[j], 16);
;                             const float r0 = v[j] * cc[j] - other * sn[j], r1 = v[j] * cc[j] + other * sn[j];
;                             v[j] = fq == 0 ? r0 : (fq == 1 ? r1 : v[j]);
;                         }
;                     }
.LBB0_1155:
	v_bitop3_b32 v56, s74, v180, v172 bitop3:0xc8
	v_lshlrev_b32_e32 v152, 6, v56
	v_lshl_add_u64 v[40:41], s[70:71], 0, v[152:153]
	s_andn2_b64 vcc, exec, s[58:59]
	v_lshl_add_u64 v[50:51], v[40:41], 0, s[34:35]
	s_cbranch_vccnz .LBB0_1205
	global_load_dwordx4 v[44:47], v[50:51], off offset:16
	global_load_dwordx4 v[0:3], v[50:51], off
	global_load_dwordx4 v[40:43], v[50:51], off offset:48
	global_load_dwordx4 v[4:7], v[50:51], off offset:32
	v_cmp_eq_u32_e32 vcc, 0, v168
	v_and_b32_e32 v237, 1, v168
	v_bfrev_b32_e32 v239, 1
	v_cmp_eq_u32_e64 s[52:53], 1, v237
	v_cmp_gt_u32_e64 s[58:59], 2, v168
	v_cndmask_b32_e32 v238, 0, v239, vcc
	v_mov_b32_e32 v248, v8
	v_mov_b32_e32 v252, v8
	v_mov_b32_e32 v249, v9
	v_mov_b32_e32 v253, v9
	v_mov_b32_e32 v250, v10
	v_mov_b32_e32 v254, v10
	v_mov_b32_e32 v251, v11
	v_mov_b32_e32 v255, v11
	v_permlane16_swap_b32_e32 v248, v252
	v_permlane16_swap_b32_e32 v249, v253
	v_permlane16_swap_b32_e32 v250, v254
	v_permlane16_swap_b32_e32 v251, v255
	s_nop 1
	v_cndmask_b32_e64 v248, v252, v248, s[52:53]
	v_cndmask_b32_e64 v249, v253, v249, s[52:53]
	v_cndmask_b32_e64 v250, v254, v250, s[52:53]
	v_cndmask_b32_e64 v251, v255, v251, s[52:53]
	s_waitcnt vmcnt(0)
	v_mul_f32_e32 v252, v8, v0
	v_xor_b32_e32 v237, v238, v1
	v_mul_f32_e32 v248, v248, v237
	v_add_f32_e32 v248, v252, v248
	v_cndmask_b32_e64 v8, v8, v248, s[58:59]
	v_mul_f32_e32 v253, v9, v2
	v_xor_b32_e32 v237, v238, v3
	v_mul_f32_e32 v249, v249, v237
	v_add_f32_e32 v249, v253, v249
	v_cndmask_b32_e64 v9, v9, v249, s[58:59]
	v_mul_f32_e32 v254, v10, v44
	v_xor_b32_e32 v237, v238, v45
	v_mul_f32_e32 v250, v250, v237
	v_add_f32_e32 v250, v254, v250
	v_cndmask_b32_e64 v10, v10, v250, s[58:59]
	v_mul_f32_e32 v255, v11, v46
	v_xor_b32_e32 v237, v238, v47
	v_mul_f32_e32 v251, v251, v237
	v_add_f32_e32 v251, v255, v251
	v_cndmask_b32_e64 v11, v11, v251, s[58:59]
	v_mov_b32_e32 v248, v12
	v_mov_b32_e32 v252, v12
	v_mov_b32_e32 v249, v13
	v_mov_b32_e32 v253, v13
	v_mov_b32_e32 v250, v14
	v_mov_b32_e32 v254, v14
	v_mov_b32_e32 v251, v15
	v_mov_b32_e32 v255, v15
	v_permlane16_swap_b32_e32 v248, v252
	v_permlane16_swap_b32_e32 v249, v253
	v_permlane16_swap_b32_e32 v250, v254
	v_permlane16_swap_b32_e32 v251, v255
	s_nop 1
	v_cndmask_b32_e64 v248, v252, v248, s[52:53]
	v_cndmask_b32_e64 v249, v253, v249, s[52:53]
	v_cndmask_b32_e64 v250, v254, v250, s[52:53]
	v_cndmask_b32_e64 v251, v255, v251, s[52:53]
	v_mul_f32_e32 v252, v12, v4
	v_xor_b32_e32 v237, v238, v5
	v_mul_f32_e32 v248, v248, v237
	v_add_f32_e32 v248, v252, v248
	v_cndmask_b32_e64 v12, v12, v248, s[58:59]
	v_mul_f32_e32 v253, v13, v6
	v_xor_b32_e32 v237, v238, v7
	v_mul_f32_e32 v249, v249, v237
	v_add_f32_e32 v249, v253, v249
	v_cndmask_b32_e64 v13, v13, v249, s[58:59]
	v_mul_f32_e32 v254, v14, v40
	v_xor_b32_e32 v237, v238, v41
	v_mul_f32_e32 v250, v250, v237
	v_add_f32_e32 v250, v254, v250
	v_cndmask_b32_e64 v14, v14, v250, s[58:59]
	v_mul_f32_e32 v255, v15, v42
	v_xor_b32_e32 v237, v238, v43
	v_mul_f32_e32 v251, v251, v237
	v_add_f32_e32 v251, v255, v251
	v_cndmask_b32_e64 v15, v15, v251, s[58:59]
	v_mov_b64_e32 v[0:1], v[8:9]
	v_mov_b64_e32 v[2:3], v[10:11]
	v_mov_b64_e32 v[4:5], v[12:13]
	v_mov_b64_e32 v[6:7], v[14:15]

;     DI void operator()(const pg8::f32x4 (&acc)[2][2][4][2], const pg8::Unit& u, int wr, int wc, int fr, int fq) const {
;     ...
;                     for (int j = 0; j < 4; ++j) { v[j] = acc[ai][bj][m][0][j] * rsq; v[4 + j] = acc[ai][bj][m][1][j] * rsq; }
;                     if (do_rope) {
;                         const f32x4* cs = (const f32x4*)(rope + (size_t)pos * 16);
;                         const f32x4 c01 = cs[0], c23 = cs[1], c45 = cs[2], c67 = cs[3];
;                         const float cc[8] = {c01.x, c01.z, c23.x, c23.z, c45.x, c45.z, c67.x, c67.z};
;                         const float sn[8] = {c01.y, c01.w, c23.y, c23.w, c45.y, c45.w, c67.y, c67.w};
; #pragma unroll
;                         for (int j = 0; j < 8; ++j) {
;                             const float other = __shfl_xor(v[j], 16);
;                             const float r0 = v[j] * cc[j] - other * sn[j], r1 = v[j] * cc[j] + other * sn[j];
;                             v[j] = fq == 0 ? r0 : (fq == 1 ? r1 : v[j]);
;                         }
;                     }
.LBB0_1246:
	global_load_dwordx4 v[36:39], v[50:51], off offset:16
	global_load_dwordx4 v[0:3], v[50:51], off
	global_load_dwordx4 v[32:35], v[50:51], off offset:48
	global_load_dwordx4 v[4:7], v[50:51], off offset:32
	v_cmp_eq_u32_e32 vcc, 0, v168
	v_and_b32_e32 v237, 1, v168
	v_bfrev_b32_e32 v239, 1
	v_cmp_eq_u32_e64 s[52:53], 1, v237
	v_cmp_gt_u32_e64 s[58:59], 2, v168
	v_cndmask_b32_e32 v238, 0, v239, vcc
	v_mov_b32_e32 v248, v8
	v_mov_b32_e32 v252, v8
	v_mov_b32_e32 v249, v9
	v_mov_b32_e32 v253, v9
	v_mov_b32_e32 v250, v10
	v_mov_b32_e32 v254, v10
	v_mov_b32_e32 v251, v11
	v_mov_b32_e32 v255, v11
	v_permlane16_swap_b32_e32 v248, v252
	v_permlane16_swap_b32_e32 v249, v253
	v_permlane16_swap_b32_e32 v250, v254
	v_permlane16_swap_b32_e32 v251, v255
	s_nop 1
	v_cndmask_b32_e64 v248, v252, v248, s[52:53]
	v_cndmask_b32_e64 v249, v253, v249, s[52:53]
	v_cndmask_b32_e64 v250, v254, v250, s[52:53]
	v_cndmask_b32_e64 v251, v255, v251, s[52:53]
	s_waitcnt vmcnt(0)
	v_mul_f32_e32 v252, v8, v0
	v_xor_b32_e32 v237, v238, v1
	v_mul_f32_e32 v248, v248, v237
	v_add_f32_e32 v248, v252, v248
	v_cndmask_b32_e64 v8, v8, v248, s[58:59]
	v_mul_f32_e32 v253, v9, v2
	v_xor_b32_e32 v237, v238, v3
	v_mul_f32_e32 v249, v249, v237
	v_add_f32_e32 v249, v253, v249
	v_cndmask_b32_e64 v9, v9, v249, s[58:59]
	v_mul_f32_e32 v254, v10, v36
	v_xor_b32_e32 v237, v238, v37
	v_mul_f32_e32 v250, v250, v237
	v_add_f32_e32 v250, v254, v250
	v_cndmask_b32_e64 v10, v10, v250, s[58:59]
	v_mul_f32_e32 v255, v11, v38
	v_xor_b32_e32 v237, v238, v39
	v_mul_f32_e32 v251, v251, v237
	v_add_f32_e32 v251, v255, v251
	v_cndmask_b32_e64 v11, v11, v251, s[58:59]
	v_mov_b32_e32 v248, v12
	v_mov_b32_e32 v252, v12
	v_mov_b32_e32 v249, v13
	v_mov_b32_e32 v253, v13
	v_mov_b32_e32 v250, v14
	v_mov_b32_e32 v254, v14
	v_mov_b32_e32 v251, v15
	v_mov_b32_e32 v255, v15
	v_permlane16_swap_b32_e32 v248, v252
	v_permlane16_swap_b32_e32 v249, v253
	v_permlane16_swap_b32_e32 v250, v254
	v_permlane16_swap_b32_e32 v251, v255
	s_nop 1
	v_cndmask_b32_e64 v248, v252, v248, s[52:53]
	v_cndmask_b32_e64 v249, v253, v249, s[52:53]
	v_cndmask_b32_e64 v250, v254, v250, s[52:53]
	v_cndmask_b32_e64 v251, v255, v251, s[52:53]
	v_mul_f32_e32 v252, v12, v4
	v_xor_b32_e32 v237, v238, v5
	v_mul_f32_e32 v248, v248, v237
	v_add_f32_e32 v248, v252, v248
	v_cndmask_b32_e64 v12, v12, v248, s[58:59]
	v_mul_f32_e32 v253, v13, v6
	v_xor_b32_e32 v237, v238, v7
	v_mul_f32_e32 v249, v249, v237
	v_add_f32_e32 v249, v253, v249
	v_cndmask_b32_e64 v13, v13, v249, s[58:59]
	v_mul_f32_e32 v254, v14, v32
	v_xor_b32_e32 v237, v238, v33
	v_mul_f32_e32 v250, v250, v237
	v_add_f32_e32 v250, v254, v250
	v_cndmask_b32_e64 v14, v14, v250, s[58:59]
	v_mul_f32_e32 v255, v15, v34
	v_xor_b32_e32 v237, v238, v35
	v_mul_f32_e32 v251, v251, v237
	v_add_f32_e32 v251, v255, v251
	v_cndmask_b32_e64 v15, v15, v251, s[58:59]
	v_mov_b64_e32 v[0:1], v[8:9]
	v_mov_b64_e32 v[2:3], v[10:11]
	v_mov_b64_e32 v[4:5], v[12:13]
	v_mov_b64_e32 v[6:7], v[14:15]
	s_and_b64 vcc, exec, s[8:9]
	s_mov_b64 s[58:59], -1
	s_cbranch_vccz .LBB0_1238

;     DI void operator()(const pg8::f32x4 (&acc)[2][2][4][2], const pg8::Unit& u, int wr, int wc, int fr, int fq) const {
;     ...
;                 const int pos = 16 + (tok & 4095), b = tok >> 12, s = tok & 4095;
; #pragma unroll
;                 for (int bj = 0; bj < 2; ++bj) {
;                     const int nb = nc0 + bj * 128 + wc * 32 + 8 * fq;
;                     float v[8];
; #pragma unroll
;                     for (int j = 0; j < 4; ++j) { v[j] = acc[ai][bj][m][0][j] * rsq; v[4 + j] = acc[ai][bj][m][1][j] * rsq; }
;                     if (do_rope) {
;                         const f32x4* cs = (const f32x4*)(rope + (size_t)pos * 16);
;                         const f32x4 c01 = cs[0], c23 = cs[1], c45 = cs[2], c67 = cs[3];
;                         const float cc[8] = {c01.x, c01.z, c23.x, c23.z, c45.x, c45.z, c67.x, c67.z};
;                         const float sn[8] = {c01.y, c01.w, c23.y, c23.w, c45.y, c45.w, c67.y, c67.w};
; #pragma unroll
;                         for (int j = 0; j < 8; ++j) {
;                             const float other = __shfl_xor(v[j], 16);
;                             const float r0 = v[j] * cc[j] - other * sn[j], r1 = v[j] * cc[j] + other * sn[j];
;                             v[j] = fq == 0 ? r0 : (fq == 1 ? r1 : v[j]);
;                         }
;                     }
.LBB0_1299:
	v_bitop3_b32 v40, s74, v181, v173 bitop3:0xc8
	v_lshlrev_b32_e32 v152, 6, v40
	v_lshl_add_u64 v[24:25], s[70:71], 0, v[152:153]
	s_andn2_b64 vcc, exec, s[10:11]
	v_lshl_add_u64 v[34:35], v[24:25], 0, s[34:35]
	s_cbranch_vccnz .LBB0_1349
	global_load_dwordx4 v[28:31], v[34:35], off offset:16
	global_load_dwordx4 v[0:3], v[34:35], off
	global_load_dwordx4 v[24:27], v[34:35], off offset:48
	global_load_dwordx4 v[4:7], v[34:35], off offset:32
	v_cmp_eq_u32_e32 vcc, 0, v168
	v_and_b32_e32 v237, 1, v168
	v_bfrev_b32_e32 v239, 1
	v_cmp_eq_u32_e64 s[10:11], 1, v237
	v_cmp_gt_u32_e64 s[58:59], 2, v168
	v_cndmask_b32_e32 v238, 0, v239, vcc
	v_mov_b32_e32 v248, v8
	v_mov_b32_e32 v252, v8
	v_mov_b32_e32 v249, v9
	v_mov_b32_e32 v253, v9
	v_mov_b32_e32 v250, v10
	v_mov_b32_e32 v254, v10
	v_mov_b32_e32 v251, v11
	v_mov_b32_e32 v255, v11
	v_permlane16_swap_b32_e32 v248, v252
	v_permlane16_swap_b32_e32 v249, v253
	v_permlane16_swap_b32_e32 v250, v254
	v_permlane16_swap_b32_e32 v251, v255
	s_nop 1
	v_cndmask_b32_e64 v248, v252, v248, s[10:11]
	v_cndmask_b32_e64 v249, v253, v249, s[10:11]
	v_cndmask_b32_e64 v250, v254, v250, s[10:11]
	v_cndmask_b32_e64 v251, v255, v251, s[10:11]
	s_waitcnt vmcnt(0)
	v_mul_f32_e32 v252, v8, v0
	v_xor_b32_e32 v237, v238, v1
	v_mul_f32_e32 v248, v248, v237
	v_add_f32_e32 v248, v252, v248
	v_cndmask_b32_e64 v8, v8, v248, s[58:59]
	v_mul_f32_e32 v253, v9, v2
	v_xor_b32_e32 v237, v238, v3
	v_mul_f32_e32 v249, v249, v237
	v_add_f32_e32 v249, v253, v249
	v_cndmask_b32_e64 v9, v9, v249, s[58:59]
	v_mul_f32_e32 v254, v10, v28
	v_xor_b32_e32 v237, v238, v29
	v_mul_f32_e32 v250, v250, v237
	v_add_f32_e32 v250, v254, v250
	v_cndmask_b32_e64 v10, v10, v250, s[58:59]
	v_mul_f32_e32 v255, v11, v30
	v_xor_b32_e32 v237, v238, v31
	v_mul_f32_e32 v251, v251, v237
	v_add_f32_e32 v251, v255, v251
	v_cndmask_b32_e64 v11, v11, v251, s[58:59]
	v_mov_b32_e32 v248, v12
	v_mov_b32_e32 v252, v12
	v_mov_b32_e32 v249, v13
	v_mov_b32_e32 v253, v13
	v_mov_b32_e32 v250, v14
	v_mov_b32_e32 v254, v14
	v_mov_b32_e32 v251, v15
	v_mov_b32_e32 v255, v15
	v_permlane16_swap_b32_e32 v248, v252
	v_permlane16_swap_b32_e32 v249, v253
	v_permlane16_swap_b32_e32 v250, v254
	v_permlane16_swap_b32_e32 v251, v255
	s_nop 1
	v_cndmask_b32_e64 v248, v252, v248, s[10:11]
	v_cndmask_b32_e64 v249, v253, v249, s[10:11]
	v_cndmask_b32_e64 v250, v254, v250, s[10:11]
	v_cndmask_b32_e64 v251, v255, v251, s[10:11]
	v_mul_f32_e32 v252, v12, v4
	v_xor_b32_e32 v237, v238, v5
	v_mul_f32_e32 v248, v248, v237
	v_add_f32_e32 v248, v252, v248
	v_cndmask_b32_e64 v12, v12, v248, s[58:59]
	v_mul_f32_e32 v253, v13, v6
	v_xor_b32_e32 v237, v238, v7
	v_mul_f32_e32 v249, v249, v237
	v_add_f32_e32 v249, v253, v249
	v_cndmask_b32_e64 v13, v13, v249, s[58:59]
	v_mul_f32_e32 v254, v14, v24
	v_xor_b32_e32 v237, v238, v25
	v_mul_f32_e32 v250, v250, v237
	v_add_f32_e32 v250, v254, v250
	v_cndmask_b32_e64 v14, v14, v250, s[58:59]
	v_mul_f32_e32 v255, v15, v26
	v_xor_b32_e32 v237, v238, v27
	v_mul_f32_e32 v251, v251, v237
	v_add_f32_e32 v251, v255, v251
	v_cndmask_b32_e64 v15, v15, v251, s[58:59]
	v_mov_b64_e32 v[0:1], v[8:9]
	v_mov_b64_e32 v[2:3], v[10:11]
	v_mov_b64_e32 v[4:5], v[12:13]
	v_mov_b64_e32 v[6:7], v[14:15]

;     DI void operator()(const pg8::f32x4 (&acc)[2][2][4][2], const pg8::Unit& u, int wr, int wc, int fr, int fq) const {
;     ...
;                     for (int j = 0; j < 4; ++j) { v[j] = acc[ai][bj][m][0][j] * rsq; v[4 + j] = acc[ai][bj][m][1][j] * rsq; }
;                     if (do_rope) {
;                         const f32x4* cs = (const f32x4*)(rope + (size_t)pos * 16);
;                         const f32x4 c01 = cs[0], c23 = cs[1], c45 = cs[2], c67 = cs[3];
;                         const float cc[8] = {c01.x, c01.z, c23.x, c23.z, c45.x, c45.z, c67.x, c67.z};
;                         const float sn[8] = {c01.y, c01.w, c23.y, c23.w, c45.y, c45.w, c67.y, c67.w};
; #pragma unroll
;                         for (int j = 0; j < 8; ++j) {
;                             const float other = __shfl_xor(v[j], 16);
;                             const float r0 = v[j] * cc[j] - other * sn[j], r1 = v[j] * cc[j] + other * sn[j];
;                             v[j] = fq == 0 ? r0 : (fq == 1 ? r1 : v[j]);
;                         }
;                     }
.LBB0_1390:
	global_load_dwordx4 v[20:23], v[34:35], off offset:16
	global_load_dwordx4 v[0:3], v[34:35], off
	global_load_dwordx4 v[16:19], v[34:35], off offset:48
	global_load_dwordx4 v[4:7], v[34:35], off offset:32
	v_cmp_eq_u32_e32 vcc, 0, v168
	v_and_b32_e32 v237, 1, v168
	v_bfrev_b32_e32 v239, 1
	v_cmp_eq_u32_e64 s[6:7], 1, v237
	v_cmp_gt_u32_e64 s[10:11], 2, v168
	v_cndmask_b32_e32 v238, 0, v239, vcc
	v_mov_b32_e32 v248, v8
	v_mov_b32_e32 v252, v8
	v_mov_b32_e32 v249, v9
	v_mov_b32_e32 v253, v9
	v_mov_b32_e32 v250, v10
	v_mov_b32_e32 v254, v10
	v_mov_b32_e32 v251, v11
	v_mov_b32_e32 v255, v11
	v_permlane16_swap_b32_e32 v248, v252
	v_permlane16_swap_b32_e32 v249, v253
	v_permlane16_swap_b32_e32 v250, v254
	v_permlane16_swap_b32_e32 v251, v255
	s_nop 1
	v_cndmask_b32_e64 v248, v252, v248, s[6:7]
	v_cndmask_b32_e64 v249, v253, v249, s[6:7]
	v_cndmask_b32_e64 v250, v254, v250, s[6:7]
	v_cndmask_b32_e64 v251, v255, v251, s[6:7]
	s_waitcnt vmcnt(0)
	v_mul_f32_e32 v252, v8, v0
	v_xor_b32_e32 v237, v238, v1
	v_mul_f32_e32 v248, v248, v237
	v_add_f32_e32 v248, v252, v248
	v_cndmask_b32_e64 v8, v8, v248, s[10:11]
	v_mul_f32_e32 v253, v9, v2
	v_xor_b32_e32 v237, v238, v3
	v_mul_f32_e32 v249, v249, v237
	v_add_f32_e32 v249, v253, v249
	v_cndmask_b32_e64 v9, v9, v249, s[10:11]
	v_mul_f32_e32 v254, v10, v20
	v_xor_b32_e32 v237, v238, v21
	v_mul_f32_e32 v250, v250, v237
	v_add_f32_e32 v250, v254, v250
	v_cndmask_b32_e64 v10, v10, v250, s[10:11]
	v_mul_f32_e32 v255, v11, v22
	v_xor_b32_e32 v237, v238, v23
	v_mul_f32_e32 v251, v251, v237
	v_add_f32_e32 v251, v255, v251
	v_cndmask_b32_e64 v11, v11, v251, s[10:11]
	v_mov_b32_e32 v248, v12
	v_mov_b32_e32 v252, v12
	v_mov_b32_e32 v249, v13
	v_mov_b32_e32 v253, v13
	v_mov_b32_e32 v250, v14
	v_mov_b32_e32 v254, v14
	v_mov_b32_e32 v251, v15
	v_mov_b32_e32 v255, v15
	v_permlane16_swap_b32_e32 v248, v252
	v_permlane16_swap_b32_e32 v249, v253
	v_permlane16_swap_b32_e32 v250, v254
	v_permlane16_swap_b32_e32 v251, v255
	s_nop 1
	v_cndmask_b32_e64 v248, v252, v248, s[6:7]
	v_cndmask_b32_e64 v249, v253, v249, s[6:7]
	v_cndmask_b32_e64 v250, v254, v250, s[6:7]
	v_cndmask_b32_e64 v251, v255, v251, s[6:7]
	v_mul_f32_e32 v252, v12, v4
	v_xor_b32_e32 v237, v238, v5
	v_mul_f32_e32 v248, v248, v237
	v_add_f32_e32 v248, v252, v248
	v_cndmask_b32_e64 v12, v12, v248, s[10:11]
	v_mul_f32_e32 v253, v13, v6
	v_xor_b32_e32 v237, v238, v7
	v_mul_f32_e32 v249, v249, v237
	v_add_f32_e32 v249, v253, v249
	v_cndmask_b32_e64 v13, v13, v249, s[10:11]
	v_mul_f32_e32 v254, v14, v16
	v_xor_b32_e32 v237, v238, v17
	v_mul_f32_e32 v250, v250, v237
	v_add_f32_e32 v250, v254, v250
	v_cndmask_b32_e64 v14, v14, v250, s[10:11]
	v_mul_f32_e32 v255, v15, v18
	v_xor_b32_e32 v237, v238, v19
	v_mul_f32_e32 v251, v251, v237
	v_add_f32_e32 v251, v255, v251
	v_cndmask_b32_e64 v15, v15, v251, s[10:11]
	v_mov_b64_e32 v[0:1], v[8:9]
	v_mov_b64_e32 v[2:3], v[10:11]
	v_mov_b64_e32 v[4:5], v[12:13]
	v_mov_b64_e32 v[6:7], v[14:15]
	s_and_b64 vcc, exec, s[8:9]
	s_mov_b64 s[6:7], -1
	s_cbranch_vccz .LBB0_1382
